# LN1 router: the 20 logit accumulators folded four-per-register during the row reduction (row_mirror/row_half_mirror with bank masks + quad_perm), 40 DPP adds instead of 80; readlanes unchanged in plac
# speedup vs baseline: 1.0352x; 1.0027x over previous
.LBB0_552:
	s_add_i32 s23, s7, 1
	s_waitcnt vmcnt(0)
	v_mov_b64_e32 v[38:39], v[84:85]
	v_mov_b64_e32 v[32:33], v[92:93]
	v_mov_b64_e32 v[34:35], v[90:91]
	v_mov_b64_e32 v[36:37], v[88:89]
	v_mov_b32_e32 v0, s23
	v_min_u32_e32 v0, 15, v0
	v_mov_b32_e32 v1, 0
	v_lshl_add_u64 v[0:1], v[82:83], 0, v[0:1]
	v_lshlrev_b64 v[2:3], 12, v[0:1]
	v_lshlrev_b64 v[0:1], 11, v[0:1]
	v_lshl_add_u64 v[12:13], v[62:63], 0, v[2:3]
	v_lshl_add_u64 v[92:93], v[64:65], 0, v[0:1]
	global_load_dwordx4 v[0:3], v[12:13], off
	global_load_dwordx2 v[84:85], v[92:93], off
	global_load_dwordx4 v[4:7], v[12:13], off offset:1024
	global_load_dwordx2 v[88:89], v[92:93], off offset:512
	global_load_dwordx4 v[8:11], v[12:13], off offset:2048
	global_load_dwordx2 v[90:91], v[92:93], off offset:1024
	s_nop 0
	global_load_dwordx4 v[12:15], v[12:13], off offset:3072
	s_nop 0
	global_load_dwordx2 v[92:93], v[92:93], off offset:1536
	v_lshlrev_b32_e32 v40, 16, v38
	v_and_b32_e32 v41, 0xffff0000, v38
	v_lshlrev_b32_e32 v38, 16, v39
	v_and_b32_e32 v39, 0xffff0000, v39
	v_lshlrev_b32_e32 v54, 16, v36
	v_and_b32_e32 v55, 0xffff0000, v36
	v_lshlrev_b32_e32 v94, 16, v37
	v_and_b32_e32 v95, 0xffff0000, v37
	v_lshlrev_b32_e32 v96, 16, v34
	v_and_b32_e32 v97, 0xffff0000, v34
	v_lshlrev_b32_e32 v100, 16, v35
	v_and_b32_e32 v101, 0xffff0000, v35
	v_lshlrev_b32_e32 v102, 16, v32
	v_and_b32_e32 v103, 0xffff0000, v32
	v_lshlrev_b32_e32 v104, 16, v33
	v_and_b32_e32 v105, 0xffff0000, v33
	v_pk_fma_f32 v[106:107], v[30:31], s[22:23], v[38:39] op_sel_hi:[1,0,1]
	ds_read_b128 v[30:33], v234
	ds_read_b128 v[34:37], v234 offset:4096
	v_pk_fma_f32 v[28:29], v[28:29], s[22:23], v[40:41] op_sel_hi:[1,0,1]
	v_pk_fma_f32 v[20:21], v[20:21], s[22:23], v[54:55] op_sel_hi:[1,0,1]
	v_add_f32_e32 v38, v28, v29
	v_add_f32_e32 v38, v38, v106
	v_pk_fma_f32 v[22:23], v[22:23], s[22:23], v[94:95] op_sel_hi:[1,0,1]
	v_add_f32_e32 v54, v20, v21
	v_pk_fma_f32 v[24:25], v[24:25], s[22:23], v[96:97] op_sel_hi:[1,0,1]
	v_add_f32_e32 v38, v107, v38
	v_add_f32_e32 v54, v54, v22
	v_pk_fma_f32 v[26:27], v[26:27], s[22:23], v[100:101] op_sel_hi:[1,0,1]
	v_add_f32_e32 v55, v24, v25
	v_add_f32_e32 v98, 0, v38
	v_add_f32_e32 v54, v23, v54
	v_add_f32_e32 v55, v55, v26
	v_add_f32_e32 v54, v98, v54
	v_add_f32_e32 v55, v27, v55
	v_pk_fma_f32 v[16:17], v[16:17], s[22:23], v[102:103] op_sel_hi:[1,0,1]
	v_add_f32_e32 v54, v54, v55
	v_pk_fma_f32 v[18:19], v[18:19], s[22:23], v[104:105] op_sel_hi:[1,0,1]
	v_add_f32_e32 v55, v16, v17
	v_add_f32_e32 v55, v55, v18
	v_add_f32_e32 v55, v19, v55
	v_add_f32_e32 v54, v54, v55
	ds_read_b128 v[38:41], v60
	ds_read_b128 v[42:45], v60 offset:4096
	ds_read_b128 v[46:49], v60 offset:8192
	ds_read_b128 v[50:53], v60 offset:12288
	ds_read_b128 v[108:111], v60 offset:16384
	ds_read_b128 v[122:125], v60 offset:20480
	ds_read_b128 v[130:133], v60 offset:24576
	ds_read_b128 v[134:137], v60 offset:28672
	ds_read_b128 v[138:141], v60 offset:32768
	ds_read_b128 v[142:145], v60 offset:36864
	ds_read_b128 v[146:149], v60 offset:40960
	ds_read_b128 v[150:153], v60 offset:45056
	ds_read_b128 v[154:157], v60 offset:49152
	v_add_f32_dpp v54, v54, v54 quad_perm:[1,0,3,2] row_mask:0xf bank_mask:0xf bound_ctrl:1
	s_nop 1
	v_add_f32_dpp v54, v54, v54 quad_perm:[2,3,0,1] row_mask:0xf bank_mask:0xf bound_ctrl:1
	s_nop 1
	v_add_f32_dpp v54, v54, v54 row_half_mirror row_mask:0xf bank_mask:0xf bound_ctrl:1
	s_nop 1
	v_add_f32_dpp v54, v54, v54 row_mirror row_mask:0xf bank_mask:0xf bound_ctrl:1
	s_nop 0
	v_readlane_b32 s2, v54, 16
	v_readlane_b32 s4, v54, 48
	v_readlane_b32 s0, v54, 0
	v_readlane_b32 s1, v54, 32
	v_mov_b32_e32 v54, s2
	v_mov_b32_e32 v55, s4
	v_pk_add_f32 v[54:55], s[0:1], v[54:55]
	s_nop 0
	v_add_f32_e32 v54, v54, v55
	v_mul_f32_e32 v54, 0x3a800000, v54
	v_pk_add_f32 v[28:29], v[28:29], v[54:55] op_sel_hi:[1,0] neg_lo:[0,1] neg_hi:[0,1]
	v_pk_add_f32 v[126:127], v[106:107], v[54:55] op_sel_hi:[1,0] neg_lo:[0,1] neg_hi:[0,1]
	v_pk_mul_f32 v[104:105], v[28:29], v[28:29]
	v_pk_mul_f32 v[106:107], v[126:127], v[126:127]
	v_pk_add_f32 v[158:159], v[20:21], v[54:55] op_sel_hi:[1,0] neg_lo:[0,1] neg_hi:[0,1]
	v_pk_add_f32 v[160:161], v[22:23], v[54:55] op_sel_hi:[1,0] neg_lo:[0,1] neg_hi:[0,1]
	v_pk_add_f32 v[100:101], v[24:25], v[54:55] op_sel_hi:[1,0] neg_lo:[0,1] neg_hi:[0,1]
	v_pk_add_f32 v[102:103], v[26:27], v[54:55] op_sel_hi:[1,0] neg_lo:[0,1] neg_hi:[0,1]
	v_pk_add_f32 v[94:95], v[16:17], v[54:55] op_sel_hi:[1,0] neg_lo:[0,1] neg_hi:[0,1]
	v_pk_add_f32 v[96:97], v[18:19], v[54:55] op_sel_hi:[1,0] neg_lo:[0,1] neg_hi:[0,1]
	v_add_f32_e32 v54, v104, v105
	v_add_f32_e32 v54, v106, v54
	v_pk_mul_f32 v[20:21], v[158:159], v[158:159]
	v_add_f32_e32 v54, v107, v54
	v_add_f32_e32 v20, v20, v54
	v_pk_mul_f32 v[22:23], v[160:161], v[160:161]
	v_add_f32_e32 v20, v21, v20
	v_add_f32_e32 v20, v22, v20
	v_pk_mul_f32 v[24:25], v[100:101], v[100:101]
	v_add_f32_e32 v20, v23, v20
	v_add_f32_e32 v20, v24, v20
	v_pk_mul_f32 v[26:27], v[102:103], v[102:103]
	v_add_f32_e32 v20, v25, v20
	v_add_f32_e32 v20, v26, v20
	v_pk_mul_f32 v[16:17], v[94:95], v[94:95]
	v_add_f32_e32 v20, v27, v20
	v_add_f32_e32 v16, v16, v20
	v_pk_mul_f32 v[18:19], v[96:97], v[96:97]
	v_add_f32_e32 v16, v17, v16
	v_add_f32_e32 v16, v18, v16
	v_add_f32_e32 v16, v19, v16
	s_nop 1
	v_add_f32_dpp v16, v16, v16 quad_perm:[1,0,3,2] row_mask:0xf bank_mask:0xf bound_ctrl:1
	s_nop 1
	v_add_f32_dpp v16, v16, v16 quad_perm:[2,3,0,1] row_mask:0xf bank_mask:0xf bound_ctrl:1
	s_nop 1
	v_add_f32_dpp v16, v16, v16 row_half_mirror row_mask:0xf bank_mask:0xf bound_ctrl:1
	s_nop 1
	v_add_f32_dpp v16, v16, v16 row_mirror row_mask:0xf bank_mask:0xf bound_ctrl:1
	s_nop 0
	v_readlane_b32 s2, v16, 16
	v_readlane_b32 s4, v16, 48
	v_readlane_b32 s0, v16, 0
	v_readlane_b32 s1, v16, 32
	v_mov_b32_e32 v16, s2
	v_mov_b32_e32 v17, s4
	v_pk_add_f32 v[16:17], s[0:1], v[16:17]
	s_mov_b32 s0, 0x800000
	v_add_f32_e32 v16, v16, v17
	v_fmamk_f32 v16, v16, 0x3a800000, v116
	v_cmp_gt_f32_e32 vcc, s0, v16
	v_mul_f32_e32 v17, 0x4b800000, v16
	s_nop 0
	v_cndmask_b32_e32 v16, v16, v17, vcc
	v_rsq_f32_e32 v54, v16
	ds_read_b128 v[16:19], v60 offset:53248
	s_waitcnt lgkmcnt(15)
	ds_read_b128 v[20:23], v60 offset:57344
	s_waitcnt lgkmcnt(15)
	ds_read_b128 v[24:27], v60 offset:61440
	s_waitcnt lgkmcnt(15)
	v_mul_f32_e32 v55, 0x45800000, v54
	v_cndmask_b32_e32 v98, v54, v55, vcc
	v_pk_mul_f32 v[28:29], v[28:29], v[98:99] op_sel_hi:[1,0]
	v_pk_fma_f32 v[106:107], v[30:31], v[28:29], v[34:35]
	v_pk_mul_f32 v[28:29], v[126:127], v[98:99] op_sel_hi:[1,0]
	s_waitcnt lgkmcnt(2)
	v_mul_f32_e32 v17, v107, v17
	v_pk_fma_f32 v[104:105], v[32:33], v[28:29], v[36:37]
	v_cvt_pk_bf16_f32 v28, v106, v107
	v_cvt_pk_bf16_f32 v29, v104, v105
	global_store_dwordx2 v[86:87], v[28:29], off offset:-1024
	v_mul_f32_e32 v28, v39, v107
	v_fmac_f32_e32 v28, v38, v106
	ds_read_b128 v[32:35], v234 offset:1024
	ds_read_b128 v[36:39], v234 offset:5120
	v_fmac_f32_e32 v28, v104, v40
	v_fmac_f32_e32 v28, v105, v41
	v_add_f32_e32 v54, 0, v28
	v_mul_f32_e32 v28, v107, v43
	v_fmac_f32_e32 v28, v106, v42
	v_fmac_f32_e32 v28, v104, v44
	v_fmac_f32_e32 v28, v105, v45
	v_add_f32_e32 v55, 0, v28
	v_mul_f32_e32 v28, v107, v47
	v_fmac_f32_e32 v28, v106, v46
	v_fmac_f32_e32 v28, v104, v48
	v_fmac_f32_e32 v28, v105, v49
	v_add_f32_e32 v46, 0, v28
	v_mul_f32_e32 v28, v107, v51
	v_fmac_f32_e32 v28, v106, v50
	v_fmac_f32_e32 v28, v104, v52
	v_fmac_f32_e32 v28, v105, v53
	v_add_f32_e32 v45, 0, v28
	v_mul_f32_e32 v28, v107, v109
	v_fmac_f32_e32 v28, v106, v108
	v_fmac_f32_e32 v28, v104, v110
	v_fmac_f32_e32 v28, v105, v111
	v_add_f32_e32 v44, 0, v28
	v_mul_f32_e32 v28, v107, v123
	v_fmac_f32_e32 v28, v106, v122
	v_fmac_f32_e32 v28, v104, v124
	v_fmac_f32_e32 v28, v105, v125
	v_add_f32_e32 v53, 0, v28
	v_mul_f32_e32 v28, v107, v131
	v_fmac_f32_e32 v28, v106, v130
	v_fmac_f32_e32 v28, v104, v132
	v_fmac_f32_e32 v28, v105, v133
	v_add_f32_e32 v52, 0, v28
	v_mul_f32_e32 v28, v107, v135
	v_fmac_f32_e32 v28, v106, v134
	v_fmac_f32_e32 v28, v104, v136
	v_fmac_f32_e32 v28, v105, v137
	v_add_f32_e32 v51, 0, v28
	v_mul_f32_e32 v28, v107, v139
	v_fmac_f32_e32 v28, v106, v138
	v_fmac_f32_e32 v28, v104, v140
	v_fmac_f32_e32 v28, v105, v141
	v_add_f32_e32 v50, 0, v28
	v_mul_f32_e32 v28, v107, v143
	v_fmac_f32_e32 v28, v106, v142
	v_fmac_f32_e32 v28, v104, v144
	v_fmac_f32_e32 v28, v105, v145
	v_add_f32_e32 v49, 0, v28
	v_mul_f32_e32 v28, v107, v147
	v_fmac_f32_e32 v28, v106, v146
	v_fmac_f32_e32 v28, v104, v148
	v_fmac_f32_e32 v28, v105, v149
	v_add_f32_e32 v48, 0, v28
	v_mul_f32_e32 v28, v107, v151
	v_fmac_f32_e32 v17, v106, v16
	s_waitcnt lgkmcnt(3)
	v_mul_f32_e32 v16, v107, v21
	v_fmac_f32_e32 v28, v106, v150
	v_fmac_f32_e32 v16, v106, v20
	v_fmac_f32_e32 v28, v104, v152
	v_fmac_f32_e32 v16, v104, v22
	v_fmac_f32_e32 v28, v105, v153
	v_fmac_f32_e32 v16, v105, v23
	v_add_f32_e32 v131, 0, v28
	v_mul_f32_e32 v28, v107, v155
	v_add_f32_e32 v122, 0, v16
	s_waitcnt lgkmcnt(2)
	v_mul_f32_e32 v16, v107, v25
	v_fmac_f32_e32 v28, v106, v154
	v_fmac_f32_e32 v16, v106, v24
	v_fmac_f32_e32 v28, v104, v156
	v_fmac_f32_e32 v17, v104, v18
	v_fmac_f32_e32 v16, v104, v26
	v_fmac_f32_e32 v28, v105, v157
	v_fmac_f32_e32 v17, v105, v19
	v_fmac_f32_e32 v16, v105, v27
	v_pk_mul_f32 v[40:41], v[158:159], v[98:99] op_sel_hi:[1,0]
	v_add_f32_e32 v125, 0, v28
	v_add_f32_e32 v124, 0, v17
	v_add_f32_e32 v123, 0, v16
	s_waitcnt lgkmcnt(0)
	v_pk_fma_f32 v[108:109], v[40:41], v[32:33], v[36:37]
	ds_read_b128 v[40:43], v60 offset:1024
	ds_read_b128 v[134:137], v60 offset:21504
	v_pk_mul_f32 v[32:33], v[160:161], v[98:99] op_sel_hi:[1,0]
	ds_read_b128 v[142:145], v60 offset:29696
	v_pk_fma_f32 v[110:111], v[32:33], v[34:35], v[38:39]
	s_waitcnt lgkmcnt(2)
	v_mul_f32_e32 v36, v109, v41
	v_cvt_pk_bf16_f32 v32, v108, v109
	v_cvt_pk_bf16_f32 v33, v110, v111
	v_fmac_f32_e32 v36, v108, v40
	global_store_dwordx2 v[86:87], v[32:33], off offset:-512
	ds_read_b128 v[32:35], v60 offset:5120
	v_fmac_f32_e32 v36, v110, v42
	v_fmac_f32_e32 v36, v111, v43
	v_add_f32_e32 v126, v54, v36
	s_waitcnt lgkmcnt(2)
	v_mul_f32_e32 v54, v109, v135
	s_waitcnt lgkmcnt(1)
	v_mul_f32_e32 v135, v109, v143
	v_fmac_f32_e32 v135, v108, v142
	v_fmac_f32_e32 v135, v110, v144
	v_fmac_f32_e32 v135, v111, v145
	ds_read_b128 v[144:147], v60 offset:50176
	s_waitcnt lgkmcnt(1)
	v_mul_f32_e32 v33, v109, v33
	v_fmac_f32_e32 v33, v108, v32
	v_fmac_f32_e32 v33, v110, v34
	v_fmac_f32_e32 v33, v111, v35
	ds_read_b128 v[36:39], v60 offset:9216
	v_add_f32_e32 v127, v55, v33
	ds_read_b128 v[32:35], v60 offset:13312
	ds_read_b128 v[40:43], v60 offset:17408
	ds_read_b128 v[138:141], v60 offset:25600
	v_fmac_f32_e32 v54, v108, v134
	v_fmac_f32_e32 v54, v110, v136
	s_waitcnt lgkmcnt(3)
	v_mul_f32_e32 v37, v109, v37
	s_waitcnt lgkmcnt(2)
	v_mul_f32_e32 v33, v109, v33
	v_fmac_f32_e32 v54, v111, v137
	v_fmac_f32_e32 v37, v108, v36
	v_fmac_f32_e32 v33, v108, v32
	v_add_f32_e32 v133, v53, v54
	s_waitcnt lgkmcnt(0)
	v_mul_f32_e32 v53, v109, v139
	v_fmac_f32_e32 v37, v110, v38
	v_fmac_f32_e32 v33, v110, v34
	v_mul_f32_e32 v41, v109, v41
	v_fmac_f32_e32 v53, v108, v138
	v_fmac_f32_e32 v37, v111, v39
	v_fmac_f32_e32 v33, v111, v35
	v_fmac_f32_e32 v41, v108, v40
	v_fmac_f32_e32 v53, v110, v140
	v_add_f32_e32 v129, v46, v37
	v_add_f32_e32 v130, v45, v33
	v_fmac_f32_e32 v41, v110, v42
	v_fmac_f32_e32 v53, v111, v141
	v_fmac_f32_e32 v41, v111, v43
	v_add_f32_e32 v134, v52, v53
	ds_read_b128 v[52:55], v60 offset:33792
	ds_read_b128 v[138:141], v60 offset:37888
	v_add_f32_e32 v132, v44, v41
	v_add_f32_e32 v135, v51, v135
	s_waitcnt lgkmcnt(1)
	v_mul_f32_e32 v51, v109, v53
	v_fmac_f32_e32 v51, v108, v52
	v_fmac_f32_e32 v51, v110, v54
	v_fmac_f32_e32 v51, v111, v55
	v_add_f32_e32 v136, v50, v51
	ds_read_b128 v[50:53], v60 offset:41984
	s_waitcnt lgkmcnt(1)
	v_mul_f32_e32 v54, v109, v139
	v_fmac_f32_e32 v54, v108, v138
	v_fmac_f32_e32 v54, v110, v140
	v_fmac_f32_e32 v54, v111, v141
	v_add_f32_e32 v137, v49, v54
	ds_read_b128 v[140:143], v60 offset:46080
	s_waitcnt lgkmcnt(1)
	v_mul_f32_e32 v49, v109, v51
	v_fmac_f32_e32 v49, v108, v50
	v_fmac_f32_e32 v49, v110, v52
	v_fmac_f32_e32 v49, v111, v53
	v_add_f32_e32 v138, v48, v49
	ds_read_b128 v[48:51], v234 offset:2048
	ds_read_b128 v[52:55], v234 offset:6144
	s_waitcnt lgkmcnt(2)
	v_mul_f32_e32 v139, v109, v141
	v_fmac_f32_e32 v139, v108, v140
	v_fmac_f32_e32 v139, v110, v142
	v_fmac_f32_e32 v139, v111, v143
	ds_read_b128 v[140:143], v60 offset:54272
	v_add_f32_e32 v131, v131, v139
	v_mul_f32_e32 v139, v109, v145
	v_fmac_f32_e32 v139, v108, v144
	v_fmac_f32_e32 v139, v110, v146
	v_fmac_f32_e32 v139, v111, v147
	ds_read_b128 v[144:147], v60 offset:58368
	v_add_f32_e32 v139, v125, v139
	s_waitcnt lgkmcnt(1)
	v_mul_f32_e32 v125, v109, v141
	v_fmac_f32_e32 v125, v108, v140
	v_fmac_f32_e32 v125, v110, v142
	v_fmac_f32_e32 v125, v111, v143
	ds_read_b128 v[140:143], v60 offset:62464
	v_add_f32_e32 v148, v124, v125
	s_waitcnt lgkmcnt(1)
	v_mul_f32_e32 v124, v109, v145
	v_fmac_f32_e32 v124, v108, v144
	v_fmac_f32_e32 v124, v110, v146
	v_fmac_f32_e32 v124, v111, v147
	v_add_f32_e32 v144, v122, v124
	s_waitcnt lgkmcnt(0)
	v_mul_f32_e32 v122, v109, v141
	v_fmac_f32_e32 v122, v108, v140
	v_fmac_f32_e32 v122, v110, v142
	v_fmac_f32_e32 v122, v111, v143
	v_add_f32_e32 v142, v123, v122
	v_mov_b32_e32 v122, v106
	v_mov_b32_e32 v123, v108
	v_mov_b32_e32 v108, v107
	v_mov_b32_e32 v106, v186
	v_mov_b32_e32 v124, v182
	v_mov_b32_e32 v140, v190
	v_mov_b32_e32 v125, v198
	v_mov_b32_e32 v107, v202
	v_pk_mul_f32 v[106:107], v[108:109], v[106:107]
	v_mov_b32_e32 v36, v187
	v_pk_fma_f32 v[106:107], v[122:123], v[124:125], v[106:107]
	v_mov_b32_e32 v124, v104
	v_mov_b32_e32 v125, v110
	v_mov_b32_e32 v110, v105
	v_mov_b32_e32 v104, v194
	v_mov_b32_e32 v141, v206
	v_pk_fma_f32 v[106:107], v[124:125], v[140:141], v[106:107]
	v_mov_b32_e32 v105, v210
	v_mov_b32_e32 v32, v183
	v_mov_b32_e32 v37, v203
	v_pk_mul_f32 v[24:25], v[108:109], v[36:37]
	v_pk_fma_f32 v[104:105], v[110:111], v[104:105], v[106:107]
	v_mov_b32_e32 v33, v199
	v_pk_fma_f32 v[24:25], v[122:123], v[32:33], v[24:25]
	v_mov_b32_e32 v40, v191
	v_add_f32_e32 v16, 0, v104
	v_mov_b32_e32 v41, v207
	v_pk_fma_f32 v[20:21], v[124:125], v[40:41], v[24:25]
	v_mov_b32_e32 v44, v195
	v_add_f32_e32 v107, v16, v105
	v_mov_b32_e32 v45, v211
	v_pk_fma_f32 v[16:17], v[110:111], v[44:45], v[20:21]
	v_mov_b32_e32 v20, v188
	v_add_f32_e32 v16, 0, v16
	v_mov_b32_e32 v21, v204
	v_add_f32_e32 v105, v16, v17
	v_mov_b32_e32 v16, v184
	v_mov_b32_e32 v17, v200
	v_pk_mul_f32 v[20:21], v[108:109], v[20:21]
	v_mov_b32_e32 v38, v189
	v_pk_fma_f32 v[16:17], v[122:123], v[16:17], v[20:21]
	v_mov_b32_e32 v20, v192
	v_mov_b32_e32 v21, v208
	v_pk_fma_f32 v[16:17], v[124:125], v[20:21], v[16:17]
	v_mov_b32_e32 v20, v196
	v_mov_b32_e32 v21, v212
	v_pk_fma_f32 v[16:17], v[110:111], v[20:21], v[16:17]
	v_mov_b32_e32 v34, v185
	v_add_f32_e32 v16, 0, v16
	v_add_f32_e32 v106, v16, v17
	v_mov_b32_e32 v39, v205
	v_pk_mul_f32 v[16:17], v[108:109], v[38:39]
	v_mov_b32_e32 v42, v193
	v_mov_b32_e32 v35, v201
	v_pk_fma_f32 v[16:17], v[122:123], v[34:35], v[16:17]
	v_mov_b32_e32 v46, v197
	v_mov_b32_e32 v43, v209
	v_pk_fma_f32 v[16:17], v[124:125], v[42:43], v[16:17]
	v_pk_mul_f32 v[20:21], v[102:103], v[98:99] op_sel_hi:[1,0]
	v_mov_b32_e32 v47, v213
	v_pk_fma_f32 v[16:17], v[110:111], v[46:47], v[16:17]
	v_pk_fma_f32 v[50:51], v[20:21], v[50:51], v[54:55]
	v_add_f32_e32 v16, 0, v16
	v_add_f32_e32 v104, v16, v17
	v_pk_mul_f32 v[16:17], v[100:101], v[98:99] op_sel_hi:[1,0]
	v_cvt_pk_bf16_f32 v21, v50, v51
	v_pk_fma_f32 v[48:49], v[16:17], v[48:49], v[52:53]
	ds_read_b128 v[16:19], v60 offset:2048
	v_cvt_pk_bf16_f32 v20, v48, v49
	global_store_dwordx2 v[86:87], v[20:21], off
	ds_read_b128 v[20:23], v60 offset:6144
	v_pk_mul_f32 v[46:47], v[94:95], v[98:99] op_sel_hi:[1,0]
	s_waitcnt lgkmcnt(1)
	v_mul_f32_e32 v17, v49, v17
	v_fmac_f32_e32 v17, v48, v16
	v_fmac_f32_e32 v17, v50, v18
	v_fmac_f32_e32 v17, v51, v19
	v_add_f32_e32 v42, v126, v17
	ds_read_b128 v[16:19], v60 offset:10240
	s_waitcnt lgkmcnt(1)
	v_mul_f32_e32 v21, v49, v21
	v_fmac_f32_e32 v21, v48, v20
	v_fmac_f32_e32 v21, v50, v22
	v_fmac_f32_e32 v21, v51, v23
	v_add_f32_e32 v41, v127, v21
	ds_read_b128 v[20:23], v60 offset:14336
	s_waitcnt lgkmcnt(1)
	v_mul_f32_e32 v17, v49, v17
	v_fmac_f32_e32 v17, v48, v16
	v_fmac_f32_e32 v17, v50, v18
	v_fmac_f32_e32 v17, v51, v19
	v_add_f32_e32 v40, v129, v17
	ds_read_b128 v[16:19], v60 offset:18432
	ds_read_b128 v[32:35], v234 offset:3072
	ds_read_b128 v[36:39], v234 offset:7168
	s_waitcnt lgkmcnt(3)
	v_mul_f32_e32 v21, v49, v21
	v_fmac_f32_e32 v21, v48, v20
	v_fmac_f32_e32 v21, v50, v22
	v_fmac_f32_e32 v21, v51, v23
	v_add_f32_e32 v45, v130, v21
	ds_read_b128 v[20:23], v60 offset:22528
	s_waitcnt lgkmcnt(3)
	v_mul_f32_e32 v17, v49, v17
	v_fmac_f32_e32 v17, v48, v16
	v_fmac_f32_e32 v17, v50, v18
	v_fmac_f32_e32 v17, v51, v19
	v_add_f32_e32 v44, v132, v17
	ds_read_b128 v[16:19], v60 offset:26624
	s_waitcnt lgkmcnt(1)
	v_mul_f32_e32 v21, v49, v21
	v_fmac_f32_e32 v21, v48, v20
	v_fmac_f32_e32 v21, v50, v22
	v_fmac_f32_e32 v21, v51, v23
	v_add_f32_e32 v124, v133, v21
	ds_read_b128 v[20:23], v60 offset:30720
	s_waitcnt lgkmcnt(1)
	v_mul_f32_e32 v17, v49, v17
	v_fmac_f32_e32 v17, v48, v16
	v_fmac_f32_e32 v17, v50, v18
	v_fmac_f32_e32 v17, v51, v19
	s_waitcnt lgkmcnt(0)
	v_mul_f32_e32 v21, v49, v21
	v_fmac_f32_e32 v21, v48, v20
	v_fmac_f32_e32 v21, v50, v22
	v_add_f32_e32 v123, v134, v17
	ds_read_b128 v[16:19], v60 offset:34816
	v_fmac_f32_e32 v21, v51, v23
	v_add_f32_e32 v122, v135, v21
	ds_read_b128 v[20:23], v60 offset:38912
	s_waitcnt lgkmcnt(1)
	v_mul_f32_e32 v17, v49, v17
	v_fmac_f32_e32 v17, v48, v16
	v_fmac_f32_e32 v17, v50, v18
	s_waitcnt lgkmcnt(0)
	v_mul_f32_e32 v21, v49, v21
	v_fmac_f32_e32 v21, v48, v20
	v_fmac_f32_e32 v17, v51, v19
	v_fmac_f32_e32 v21, v50, v22
	v_add_f32_e32 v111, v136, v17
	ds_read_b128 v[16:19], v60 offset:43008
	v_fmac_f32_e32 v21, v51, v23
	v_add_f32_e32 v110, v137, v21
	ds_read_b128 v[20:23], v60 offset:47104
	s_waitcnt lgkmcnt(1)
	v_mul_f32_e32 v17, v49, v17
	v_fmac_f32_e32 v17, v48, v16
	v_fmac_f32_e32 v17, v50, v18
	s_waitcnt lgkmcnt(0)
	v_mul_f32_e32 v21, v49, v21
	v_fmac_f32_e32 v21, v48, v20
	v_fmac_f32_e32 v17, v51, v19
	v_fmac_f32_e32 v21, v50, v22
	v_add_f32_e32 v109, v138, v17
	ds_read_b128 v[16:19], v60 offset:51200
	v_fmac_f32_e32 v21, v51, v23
	v_add_f32_e32 v108, v131, v21
	ds_read_b128 v[20:23], v60 offset:55296
	s_waitcnt lgkmcnt(1)
	v_mul_f32_e32 v17, v49, v17
	v_fmac_f32_e32 v17, v48, v16
	v_fmac_f32_e32 v17, v50, v18
	s_waitcnt lgkmcnt(0)
	v_mul_f32_e32 v21, v49, v21
	v_fmac_f32_e32 v21, v48, v20
	v_fmac_f32_e32 v17, v51, v19
	v_fmac_f32_e32 v21, v50, v22
	v_add_f32_e32 v103, v139, v17
	ds_read_b128 v[16:19], v60 offset:59392
	v_fmac_f32_e32 v21, v51, v23
	v_add_f32_e32 v102, v148, v21
	ds_read_b128 v[20:23], v60 offset:63488
	s_waitcnt lgkmcnt(1)
	v_mul_f32_e32 v17, v49, v17
	v_fmac_f32_e32 v17, v48, v16
	v_fmac_f32_e32 v17, v50, v18
	s_waitcnt lgkmcnt(0)
	v_mul_f32_e32 v16, v49, v21
	v_fmac_f32_e32 v16, v48, v20
	v_fmac_f32_e32 v16, v50, v22
	v_fmac_f32_e32 v17, v51, v19
	v_fmac_f32_e32 v16, v51, v23
	v_add_f32_e32 v100, v144, v17
	v_add_f32_e32 v101, v142, v16
	v_pk_fma_f32 v[52:53], v[46:47], v[32:33], v[36:37]
	v_pk_mul_f32 v[32:33], v[96:97], v[98:99] op_sel_hi:[1,0]
	ds_read_b128 v[94:97], v60 offset:3072
	v_pk_fma_f32 v[54:55], v[32:33], v[34:35], v[38:39]
	v_cvt_pk_bf16_f32 v32, v52, v53
	v_cvt_pk_bf16_f32 v33, v54, v55
	global_store_dwordx2 v[86:87], v[32:33], off offset:512
	ds_read_b128 v[32:35], v60 offset:7168
	s_waitcnt lgkmcnt(1)
	v_mul_f32_e32 v36, v53, v95
	v_fmac_f32_e32 v36, v52, v94
	v_fmac_f32_e32 v36, v54, v96
	v_fmac_f32_e32 v36, v55, v97
	v_add_f32_e32 v94, v42, v36
	ds_read_b128 v[36:39], v60 offset:11264
	ds_read_b128 v[130:133], v60 offset:15360
	s_waitcnt lgkmcnt(2)
	v_mul_f32_e32 v33, v53, v33
	v_fmac_f32_e32 v33, v52, v32
	v_fmac_f32_e32 v33, v54, v34
	s_waitcnt lgkmcnt(1)
	v_mul_f32_e32 v32, v53, v37
	v_fmac_f32_e32 v32, v52, v36
	v_fmac_f32_e32 v32, v54, v38
	v_fmac_f32_e32 v33, v55, v35
	v_fmac_f32_e32 v32, v55, v39
	v_add_f32_e32 v95, v41, v33
	v_add_f32_e32 v96, v40, v32
	ds_read_b128 v[40:43], v60 offset:19456
	s_waitcnt lgkmcnt(1)
	v_mul_f32_e32 v36, v53, v131
	v_fmac_f32_e32 v36, v52, v130
	v_fmac_f32_e32 v36, v54, v132
	v_fmac_f32_e32 v36, v55, v133
	v_add_f32_e32 v97, v45, v36
	ds_read_b128 v[130:133], v60 offset:23552
	s_waitcnt lgkmcnt(1)
	v_mul_f32_e32 v45, v53, v41
	v_fmac_f32_e32 v45, v52, v40
	v_fmac_f32_e32 v45, v54, v42
	v_fmac_f32_e32 v45, v55, v43
	v_add_f32_e32 v125, v44, v45
	ds_read_b128 v[134:137], v60 offset:27648
	s_waitcnt lgkmcnt(1)
	v_mul_f32_e32 v98, v53, v131
	v_fmac_f32_e32 v98, v52, v130
	v_fmac_f32_e32 v98, v54, v132
	v_fmac_f32_e32 v98, v55, v133
	ds_read_b128 v[130:133], v60 offset:31744
	v_add_f32_e32 v124, v124, v98
	s_waitcnt lgkmcnt(1)
	v_mul_f32_e32 v98, v53, v135
	v_fmac_f32_e32 v98, v52, v134
	v_fmac_f32_e32 v98, v54, v136
	v_fmac_f32_e32 v98, v55, v137
	ds_read_b128 v[134:137], v60 offset:35840
	v_add_f32_e32 v98, v123, v98
	s_waitcnt lgkmcnt(1)
	v_mul_f32_e32 v123, v53, v131
	v_fmac_f32_e32 v123, v52, v130
	v_fmac_f32_e32 v123, v54, v132
	v_fmac_f32_e32 v123, v55, v133
	ds_read_b128 v[130:133], v60 offset:39936
	v_add_f32_e32 v122, v122, v123
	s_waitcnt lgkmcnt(1)
	v_mul_f32_e32 v123, v53, v135
	v_fmac_f32_e32 v123, v52, v134
	v_fmac_f32_e32 v123, v54, v136
	v_fmac_f32_e32 v123, v55, v137
	ds_read_b128 v[134:137], v60 offset:44032
	v_add_f32_e32 v111, v111, v123
	s_waitcnt lgkmcnt(1)
	v_mul_f32_e32 v123, v53, v131
	v_fmac_f32_e32 v123, v52, v130
	v_fmac_f32_e32 v123, v54, v132
	v_fmac_f32_e32 v123, v55, v133
	ds_read_b128 v[130:133], v60 offset:48128
	v_add_f32_e32 v110, v110, v123
	s_waitcnt lgkmcnt(1)
	v_mul_f32_e32 v123, v53, v135
	v_fmac_f32_e32 v123, v52, v134
	v_fmac_f32_e32 v123, v54, v136
	v_fmac_f32_e32 v123, v55, v137
	ds_read_b128 v[134:137], v60 offset:52224
	v_add_f32_e32 v109, v109, v123
	s_waitcnt lgkmcnt(1)
	v_mul_f32_e32 v123, v53, v131
	v_fmac_f32_e32 v123, v52, v130
	v_fmac_f32_e32 v123, v54, v132
	v_fmac_f32_e32 v123, v55, v133
	ds_read_b128 v[130:133], v60 offset:56320
	v_add_f32_e32 v108, v108, v123
	s_waitcnt lgkmcnt(1)
	v_mul_f32_e32 v123, v53, v135
	v_fmac_f32_e32 v123, v52, v134
	v_fmac_f32_e32 v123, v54, v136
	v_fmac_f32_e32 v123, v55, v137
	ds_read_b128 v[134:137], v60 offset:60416
	v_add_f32_e32 v103, v103, v123
	s_waitcnt lgkmcnt(1)
	v_mul_f32_e32 v123, v53, v131
	v_fmac_f32_e32 v123, v52, v130
	v_fmac_f32_e32 v123, v54, v132
	v_fmac_f32_e32 v123, v55, v133
	ds_read_b128 v[130:133], v60 offset:64512
	v_add_f32_e32 v102, v102, v123
	s_waitcnt lgkmcnt(1)
	v_mul_f32_e32 v123, v53, v135
	v_fmac_f32_e32 v123, v52, v134
	v_fmac_f32_e32 v123, v54, v136
	v_fmac_f32_e32 v123, v55, v137
	v_add_f32_e32 v123, v100, v123
	s_waitcnt lgkmcnt(0)
	v_mul_f32_e32 v100, v53, v131
	v_fmac_f32_e32 v100, v52, v130
	v_fmac_f32_e32 v100, v54, v132
	v_fmac_f32_e32 v100, v55, v133
	v_add_f32_e32 v129, v101, v100
	v_mov_b32_e32 v100, v48
	v_mov_b32_e32 v101, v52
	v_mov_b32_e32 v52, v49
	v_mov_b32_e32 v48, v218
	v_mov_b32_e32 v126, v214
	v_mov_b32_e32 v130, v222
	v_mov_b32_e32 v127, v230
	v_mov_b32_e32 v49, v238
	v_pk_mul_f32 v[48:49], v[52:53], v[48:49]
	v_mov_b32_e32 v36, v219
	v_pk_fma_f32 v[48:49], v[100:101], v[126:127], v[48:49]
	v_mov_b32_e32 v126, v50
	v_mov_b32_e32 v127, v54
	v_mov_b32_e32 v131, v242
	v_pk_fma_f32 v[48:49], v[126:127], v[130:131], v[48:49]
	v_mov_b32_e32 v54, v51
	v_mov_b32_e32 v50, v226
	v_mov_b32_e32 v51, v246
	v_mov_b32_e32 v32, v215
	v_mov_b32_e32 v37, v239
	v_pk_mul_f32 v[24:25], v[52:53], v[36:37]
	v_pk_fma_f32 v[48:49], v[54:55], v[50:51], v[48:49]
	v_mov_b32_e32 v33, v231
	v_pk_fma_f32 v[24:25], v[100:101], v[32:33], v[24:25]
	v_mov_b32_e32 v40, v223
	v_add_f32_e32 v16, v107, v48
	v_mov_b32_e32 v41, v243
	v_pk_fma_f32 v[20:21], v[126:127], v[40:41], v[24:25]
	v_mov_b32_e32 v44, v227
	v_add_f32_e32 v28, v16, v49
	v_mov_b32_e32 v45, v247
	v_pk_fma_f32 v[16:17], v[54:55], v[44:45], v[20:21]
	v_mov_b32_e32 v20, v220
	v_add_f32_e32 v16, v105, v16
	v_mov_b32_e32 v21, v240
	v_add_f32_e32 v24, v16, v17
	v_mov_b32_e32 v16, v216
	v_mov_b32_e32 v17, v232
	v_pk_mul_f32 v[20:21], v[52:53], v[20:21]
	v_mov_b32_e32 v38, v221
	v_pk_fma_f32 v[16:17], v[100:101], v[16:17], v[20:21]
	v_mov_b32_e32 v20, v224
	v_mov_b32_e32 v21, v244
	v_pk_fma_f32 v[16:17], v[126:127], v[20:21], v[16:17]
	v_mov_b32_e32 v20, v228
	v_mov_b32_e32 v21, v248
	v_pk_fma_f32 v[16:17], v[54:55], v[20:21], v[16:17]
	v_mov_b32_e32 v34, v217
	v_add_f32_e32 v16, v106, v16
	v_add_f32_e32 v20, v16, v17
	v_mov_b32_e32 v39, v241
	v_pk_mul_f32 v[16:17], v[52:53], v[38:39]
	v_mov_b32_e32 v42, v225
	v_mov_b32_e32 v35, v233
	v_pk_fma_f32 v[16:17], v[100:101], v[34:35], v[16:17]
	v_mov_b32_e32 v46, v229
	v_mov_b32_e32 v43, v245
	v_pk_fma_f32 v[16:17], v[126:127], v[42:43], v[16:17]
	v_mov_b32_e32 v47, v249
	v_pk_fma_f32 v[16:17], v[54:55], v[46:47], v[16:17]
	v_add_f32_e32 v16, v104, v16
	v_add_f32_e32 v22, v16, v17
	v_add_f32_dpp v250, v24, v24 row_mirror row_mask:0xf bank_mask:0xf bound_ctrl:1
	v_add_f32_dpp v94, v94, v94 row_mirror row_mask:0xf bank_mask:0xf bound_ctrl:1
	v_add_f32_dpp v125, v125, v125 row_mirror row_mask:0xf bank_mask:0xf bound_ctrl:1
	v_add_f32_dpp v111, v111, v111 row_mirror row_mask:0xf bank_mask:0xf bound_ctrl:1
	v_add_f32_dpp v103, v103, v103 row_mirror row_mask:0xf bank_mask:0xf bound_ctrl:1
	v_add_f32_dpp v250, v20, v20 row_mirror row_mask:0xf bank_mask:0xc bound_ctrl:1
	v_add_f32_dpp v94, v95, v95 row_mirror row_mask:0xf bank_mask:0xc bound_ctrl:1
	v_add_f32_dpp v125, v124, v124 row_mirror row_mask:0xf bank_mask:0xc bound_ctrl:1
	v_add_f32_dpp v111, v110, v110 row_mirror row_mask:0xf bank_mask:0xc bound_ctrl:1
	v_add_f32_dpp v103, v102, v102 row_mirror row_mask:0xf bank_mask:0xc bound_ctrl:1
	v_add_f32_dpp v251, v28, v28 row_mirror row_mask:0xf bank_mask:0xf bound_ctrl:1
	v_add_f32_dpp v96, v96, v96 row_mirror row_mask:0xf bank_mask:0xf bound_ctrl:1
	v_add_f32_dpp v98, v98, v98 row_mirror row_mask:0xf bank_mask:0xf bound_ctrl:1
	v_add_f32_dpp v109, v109, v109 row_mirror row_mask:0xf bank_mask:0xf bound_ctrl:1
	v_add_f32_dpp v123, v123, v123 row_mirror row_mask:0xf bank_mask:0xf bound_ctrl:1
	v_add_f32_dpp v251, v22, v22 row_mirror row_mask:0xf bank_mask:0xc bound_ctrl:1
	v_add_f32_dpp v96, v97, v97 row_mirror row_mask:0xf bank_mask:0xc bound_ctrl:1
	v_add_f32_dpp v98, v122, v122 row_mirror row_mask:0xf bank_mask:0xc bound_ctrl:1
	v_add_f32_dpp v109, v108, v108 row_mirror row_mask:0xf bank_mask:0xc bound_ctrl:1
	v_add_f32_dpp v123, v129, v129 row_mirror row_mask:0xf bank_mask:0xc bound_ctrl:1
	v_add_f32_dpp v250, v250, v250 row_half_mirror row_mask:0xf bank_mask:0xf bound_ctrl:1
	v_add_f32_dpp v94, v94, v94 row_half_mirror row_mask:0xf bank_mask:0xf bound_ctrl:1
	v_add_f32_dpp v125, v125, v125 row_half_mirror row_mask:0xf bank_mask:0xf bound_ctrl:1
	v_add_f32_dpp v111, v111, v111 row_half_mirror row_mask:0xf bank_mask:0xf bound_ctrl:1
	v_add_f32_dpp v103, v103, v103 row_half_mirror row_mask:0xf bank_mask:0xf bound_ctrl:1
	v_add_f32_dpp v250, v251, v251 row_half_mirror row_mask:0xf bank_mask:0xa bound_ctrl:1
	v_add_f32_dpp v94, v96, v96 row_half_mirror row_mask:0xf bank_mask:0xa bound_ctrl:1
	v_add_f32_dpp v125, v98, v98 row_half_mirror row_mask:0xf bank_mask:0xa bound_ctrl:1
	v_add_f32_dpp v111, v109, v109 row_half_mirror row_mask:0xf bank_mask:0xa bound_ctrl:1
	v_add_f32_dpp v103, v123, v123 row_half_mirror row_mask:0xf bank_mask:0xa bound_ctrl:1
	v_add_f32_dpp v250, v250, v250 quad_perm:[1,0,3,2] row_mask:0xf bank_mask:0xf bound_ctrl:1
	v_add_f32_dpp v94, v94, v94 quad_perm:[1,0,3,2] row_mask:0xf bank_mask:0xf bound_ctrl:1
	v_add_f32_dpp v125, v125, v125 quad_perm:[1,0,3,2] row_mask:0xf bank_mask:0xf bound_ctrl:1
	v_add_f32_dpp v111, v111, v111 quad_perm:[1,0,3,2] row_mask:0xf bank_mask:0xf bound_ctrl:1
	v_add_f32_dpp v103, v103, v103 quad_perm:[1,0,3,2] row_mask:0xf bank_mask:0xf bound_ctrl:1
	v_add_f32_dpp v250, v250, v250 quad_perm:[2,3,0,1] row_mask:0xf bank_mask:0xf bound_ctrl:1
	v_add_f32_dpp v94, v94, v94 quad_perm:[2,3,0,1] row_mask:0xf bank_mask:0xf bound_ctrl:1
	v_add_f32_dpp v125, v125, v125 quad_perm:[2,3,0,1] row_mask:0xf bank_mask:0xf bound_ctrl:1
	v_add_f32_dpp v111, v111, v111 quad_perm:[2,3,0,1] row_mask:0xf bank_mask:0xf bound_ctrl:1
	v_add_f32_dpp v103, v103, v103 quad_perm:[2,3,0,1] row_mask:0xf bank_mask:0xf bound_ctrl:1
	v_readlane_b32 s2, v250, 20
	v_readlane_b32 s4, v250, 52
	v_readlane_b32 s0, v250, 4
	v_readlane_b32 s1, v250, 36
	v_mov_b32_e32 v16, s2
	v_mov_b32_e32 v17, s4
	v_readlane_b32 s2, v250, 16
	v_readlane_b32 s4, v250, 48
	v_pk_add_f32 v[16:17], s[0:1], v[16:17]
	v_readlane_b32 s0, v250, 0
	v_readlane_b32 s1, v250, 32
	v_mov_b32_e32 v18, s2
	v_mov_b32_e32 v19, s4
	v_readlane_b32 s2, v250, 24
	v_readlane_b32 s4, v250, 56
	v_pk_add_f32 v[18:19], s[0:1], v[18:19]
	v_readlane_b32 s0, v250, 8
	v_readlane_b32 s1, v250, 40
	v_mov_b32_e32 v20, s2
	v_mov_b32_e32 v21, s4
	v_pk_add_f32 v[20:21], s[0:1], v[20:21]
	v_mov_b32_e32 v25, v18
	v_add_f32_e32 v26, v20, v21
	v_mov_b32_e32 v18, v17
	v_readlane_b32 s2, v250, 28
	v_readlane_b32 s4, v250, 60
	v_readlane_b32 s0, v250, 12
	v_readlane_b32 s1, v250, 44
	v_mov_b32_e32 v20, s2
	v_mov_b32_e32 v21, s4
	v_pk_add_f32 v[20:21], s[0:1], v[20:21]
	v_add_f32_e32 v27, v20, v21
	v_readlane_b32 s20, v94, 0
	v_readlane_b32 s4, v94, 16
	v_readlane_b32 s21, v94, 32
	v_readlane_b32 s5, v94, 48
	v_readlane_b32 s91, v94, 8
	v_readlane_b32 s95, v94, 24
	v_readlane_b32 s94, v94, 40
	v_readlane_b32 s92, v94, 56
	v_readlane_b32 s6, v94, 4
	v_readlane_b32 s75, v94, 20
	v_readlane_b32 s74, v94, 36
	v_readlane_b32 s84, v94, 52
	v_readlane_b32 s97, v94, 12
	v_readlane_b32 s9, v94, 28
	v_readlane_b32 s8, v94, 44
	v_readlane_b32 s12, v94, 60
	v_readlane_b32 s59, v125, 0
	v_readlane_b32 s61, v125, 16
	v_readlane_b32 s60, v125, 32
	v_readlane_b32 s82, v125, 48
	v_readlane_b32 s52, v125, 8
	v_readlane_b32 s54, v125, 24
	v_readlane_b32 s53, v125, 40
	v_readlane_b32 s93, v125, 56
	v_readlane_b32 s85, v125, 4
	v_readlane_b32 s87, v125, 20
	v_readlane_b32 s86, v125, 36
	v_readlane_b32 s90, v125, 52
	v_readlane_b32 s13, v125, 12
	v_readlane_b32 s24, v125, 28
	v_readlane_b32 s16, v125, 44
	v_readlane_b32 s17, v125, 60
	v_readlane_b32 s83, v111, 0
	v_readlane_b32 s89, v111, 16
	v_readlane_b32 s88, v111, 32
	v_readlane_b32 s96, v111, 48
	v_readlane_b32 s55, v111, 8
	v_readlane_b32 s57, v111, 24
	v_readlane_b32 s56, v111, 40
	v_readlane_b32 s58, v111, 56
	v_readlane_b32 s46, v111, 4
	v_readlane_b32 s48, v111, 20
	v_readlane_b32 s47, v111, 36
	v_readlane_b32 s49, v111, 52
	v_readlane_b32 s38, v111, 12
	v_readlane_b32 s40, v111, 28
	v_readlane_b32 s39, v111, 44
	v_readlane_b32 s41, v111, 60
	v_readlane_b32 s34, v103, 0
	v_readlane_b32 s36, v103, 16
	v_readlane_b32 s35, v103, 32
	v_readlane_b32 s37, v103, 48
	v_readlane_b32 s29, v103, 8
	v_readlane_b32 s31, v103, 24
	v_readlane_b32 s30, v103, 40
	v_readlane_b32 s33, v103, 56
	v_readlane_b32 s25, v103, 4
	v_readlane_b32 s28, v103, 20
	v_readlane_b32 s50, v103, 36
	v_readlane_b32 s51, v103, 52
	v_mov_b32_e32 v24, v16
	v_pk_add_f32 v[16:17], v[24:25], v[18:19]
	v_mov_b32_e32 v20, v178
	v_mov_b32_e32 v21, v179
	v_mov_b32_e32 v22, v180
	v_mov_b32_e32 v23, v181
	v_add_f32_e32 v19, v26, v22
	v_pk_add_f32 v[16:17], v[16:17], v[20:21]
	v_add_f32_e32 v18, v27, v23
	v_cmp_gt_f32_e32 vcc, v17, v16
	v_mov_b32_e32 v22, 0
	v_readlane_b32 s42, v103, 12
	v_cndmask_b32_e32 v20, v16, v17, vcc
	v_cmp_gt_f32_e64 s[18:19], v19, v20
	v_cndmask_b32_e64 v21, 0, 1, vcc
	s_and_b64 s[14:15], s[18:19], exec
	v_cndmask_b32_e64 v20, v20, v19, s[18:19]
	v_cmp_ngt_f32_e64 s[0:1], v18, v20
	v_readfirstlane_b32 s2, v21
	s_cselect_b32 s2, 2, s2
	s_and_b64 s[14:15], s[0:1], exec
	s_cselect_b32 s2, s2, 3
	s_cmp_eq_u32 s2, 0
	s_cselect_b64 s[26:27], -1, 0
	s_cmp_lg_u32 s2, 0
	v_mov_b32_e32 v21, 0
	v_readlane_b32 s44, v103, 28
	v_readlane_b32 s43, v103, 44
	v_readlane_b32 s45, v103, 60
	v_cmp_gt_f32_e64 s[14:15], v18, v20
	s_waitcnt lgkmcnt(0)
	s_cbranch_scc0 .LBB0_560
	v_cndmask_b32_e64 v23, 0, 1, s[26:27]
	v_cmp_ne_u32_e64 s[20:21], 1, v23
	s_andn2_b64 vcc, exec, s[26:27]
	s_cbranch_vccz .LBB0_561

.LBB0_1676:
	s_add_i32 s21, s19, 1
	s_waitcnt vmcnt(0)
	v_mov_b64_e32 v[38:39], v[84:85]
	v_mov_b64_e32 v[32:33], v[92:93]
	v_mov_b64_e32 v[34:35], v[90:91]
	v_mov_b64_e32 v[36:37], v[88:89]
	v_mov_b32_e32 v0, s21
	v_min_u32_e32 v0, 15, v0
	v_mov_b32_e32 v1, 0
	v_lshl_add_u64 v[0:1], v[82:83], 0, v[0:1]
	v_lshlrev_b64 v[2:3], 12, v[0:1]
	v_lshlrev_b64 v[0:1], 11, v[0:1]
	v_lshl_add_u64 v[12:13], v[62:63], 0, v[2:3]
	v_lshl_add_u64 v[92:93], v[64:65], 0, v[0:1]
	global_load_dwordx4 v[0:3], v[12:13], off
	global_load_dwordx2 v[84:85], v[92:93], off
	global_load_dwordx4 v[4:7], v[12:13], off offset:1024
	global_load_dwordx2 v[88:89], v[92:93], off offset:512
	global_load_dwordx4 v[8:11], v[12:13], off offset:2048
	global_load_dwordx2 v[90:91], v[92:93], off offset:1024
	s_nop 0
	global_load_dwordx4 v[12:15], v[12:13], off offset:3072
	s_nop 0
	global_load_dwordx2 v[92:93], v[92:93], off offset:1536
	v_lshlrev_b32_e32 v40, 16, v38
	v_and_b32_e32 v41, 0xffff0000, v38
	v_lshlrev_b32_e32 v38, 16, v39
	v_and_b32_e32 v39, 0xffff0000, v39
	v_lshlrev_b32_e32 v54, 16, v36
	v_and_b32_e32 v55, 0xffff0000, v36
	v_lshlrev_b32_e32 v94, 16, v37
	v_and_b32_e32 v95, 0xffff0000, v37
	v_lshlrev_b32_e32 v96, 16, v34
	v_and_b32_e32 v97, 0xffff0000, v34
	v_lshlrev_b32_e32 v100, 16, v35
	v_and_b32_e32 v101, 0xffff0000, v35
	v_lshlrev_b32_e32 v102, 16, v32
	v_and_b32_e32 v103, 0xffff0000, v32
	v_lshlrev_b32_e32 v104, 16, v33
	v_and_b32_e32 v105, 0xffff0000, v33
	v_pk_fma_f32 v[106:107], v[30:31], s[20:21], v[38:39] op_sel_hi:[1,0,1]
	ds_read_b128 v[30:33], v234
	ds_read_b128 v[34:37], v234 offset:4096
	v_pk_fma_f32 v[28:29], v[28:29], s[20:21], v[40:41] op_sel_hi:[1,0,1]
	v_pk_fma_f32 v[20:21], v[20:21], s[20:21], v[54:55] op_sel_hi:[1,0,1]
	v_add_f32_e32 v38, v28, v29
	v_add_f32_e32 v38, v38, v106
	v_pk_fma_f32 v[22:23], v[22:23], s[20:21], v[94:95] op_sel_hi:[1,0,1]
	v_add_f32_e32 v54, v20, v21
	v_pk_fma_f32 v[24:25], v[24:25], s[20:21], v[96:97] op_sel_hi:[1,0,1]
	v_add_f32_e32 v38, v107, v38
	v_add_f32_e32 v54, v54, v22
	v_pk_fma_f32 v[26:27], v[26:27], s[20:21], v[100:101] op_sel_hi:[1,0,1]
	v_add_f32_e32 v55, v24, v25
	v_add_f32_e32 v98, 0, v38
	v_add_f32_e32 v54, v23, v54
	v_add_f32_e32 v55, v55, v26
	v_add_f32_e32 v54, v98, v54
	v_add_f32_e32 v55, v27, v55
	v_pk_fma_f32 v[16:17], v[16:17], s[20:21], v[102:103] op_sel_hi:[1,0,1]
	v_add_f32_e32 v54, v54, v55
	v_pk_fma_f32 v[18:19], v[18:19], s[20:21], v[104:105] op_sel_hi:[1,0,1]
	v_add_f32_e32 v55, v16, v17
	v_add_f32_e32 v55, v55, v18
	v_add_f32_e32 v55, v19, v55
	v_add_f32_e32 v54, v54, v55
	ds_read_b128 v[38:41], v60
	ds_read_b128 v[42:45], v60 offset:4096
	ds_read_b128 v[46:49], v60 offset:8192
	ds_read_b128 v[50:53], v60 offset:12288
	ds_read_b128 v[108:111], v60 offset:16384
	ds_read_b128 v[122:125], v60 offset:20480
	ds_read_b128 v[130:133], v60 offset:24576
	ds_read_b128 v[134:137], v60 offset:28672
	ds_read_b128 v[138:141], v60 offset:32768
	ds_read_b128 v[142:145], v60 offset:36864
	ds_read_b128 v[146:149], v60 offset:40960
	ds_read_b128 v[150:153], v60 offset:45056
	ds_read_b128 v[154:157], v60 offset:49152
	v_add_f32_dpp v54, v54, v54 quad_perm:[1,0,3,2] row_mask:0xf bank_mask:0xf bound_ctrl:1
	s_nop 1
	v_add_f32_dpp v54, v54, v54 quad_perm:[2,3,0,1] row_mask:0xf bank_mask:0xf bound_ctrl:1
	s_nop 1
	v_add_f32_dpp v54, v54, v54 row_half_mirror row_mask:0xf bank_mask:0xf bound_ctrl:1
	s_nop 1
	v_add_f32_dpp v54, v54, v54 row_mirror row_mask:0xf bank_mask:0xf bound_ctrl:1
	s_nop 0
	v_readlane_b32 s2, v54, 16
	v_readlane_b32 s10, v54, 48
	v_readlane_b32 s0, v54, 0
	v_readlane_b32 s1, v54, 32
	v_mov_b32_e32 v54, s2
	v_mov_b32_e32 v55, s10
	v_pk_add_f32 v[54:55], s[0:1], v[54:55]
	s_nop 0
	v_add_f32_e32 v54, v54, v55
	v_mul_f32_e32 v54, 0x3a800000, v54
	v_pk_add_f32 v[28:29], v[28:29], v[54:55] op_sel_hi:[1,0] neg_lo:[0,1] neg_hi:[0,1]
	v_pk_add_f32 v[126:127], v[106:107], v[54:55] op_sel_hi:[1,0] neg_lo:[0,1] neg_hi:[0,1]
	v_pk_mul_f32 v[104:105], v[28:29], v[28:29]
	v_pk_mul_f32 v[106:107], v[126:127], v[126:127]
	v_pk_add_f32 v[158:159], v[20:21], v[54:55] op_sel_hi:[1,0] neg_lo:[0,1] neg_hi:[0,1]
	v_pk_add_f32 v[160:161], v[22:23], v[54:55] op_sel_hi:[1,0] neg_lo:[0,1] neg_hi:[0,1]
	v_pk_add_f32 v[100:101], v[24:25], v[54:55] op_sel_hi:[1,0] neg_lo:[0,1] neg_hi:[0,1]
	v_pk_add_f32 v[102:103], v[26:27], v[54:55] op_sel_hi:[1,0] neg_lo:[0,1] neg_hi:[0,1]
	v_pk_add_f32 v[94:95], v[16:17], v[54:55] op_sel_hi:[1,0] neg_lo:[0,1] neg_hi:[0,1]
	v_pk_add_f32 v[96:97], v[18:19], v[54:55] op_sel_hi:[1,0] neg_lo:[0,1] neg_hi:[0,1]
	v_add_f32_e32 v54, v104, v105
	v_add_f32_e32 v54, v106, v54
	v_pk_mul_f32 v[20:21], v[158:159], v[158:159]
	v_add_f32_e32 v54, v107, v54
	v_add_f32_e32 v20, v20, v54
	v_pk_mul_f32 v[22:23], v[160:161], v[160:161]
	v_add_f32_e32 v20, v21, v20
	v_add_f32_e32 v20, v22, v20
	v_pk_mul_f32 v[24:25], v[100:101], v[100:101]
	v_add_f32_e32 v20, v23, v20
	v_add_f32_e32 v20, v24, v20
	v_pk_mul_f32 v[26:27], v[102:103], v[102:103]
	v_add_f32_e32 v20, v25, v20
	v_add_f32_e32 v20, v26, v20
	v_pk_mul_f32 v[16:17], v[94:95], v[94:95]
	v_add_f32_e32 v20, v27, v20
	v_add_f32_e32 v16, v16, v20
	v_pk_mul_f32 v[18:19], v[96:97], v[96:97]
	v_add_f32_e32 v16, v17, v16
	v_add_f32_e32 v16, v18, v16
	v_add_f32_e32 v16, v19, v16
	s_nop 1
	v_add_f32_dpp v16, v16, v16 quad_perm:[1,0,3,2] row_mask:0xf bank_mask:0xf bound_ctrl:1
	s_nop 1
	v_add_f32_dpp v16, v16, v16 quad_perm:[2,3,0,1] row_mask:0xf bank_mask:0xf bound_ctrl:1
	s_nop 1
	v_add_f32_dpp v16, v16, v16 row_half_mirror row_mask:0xf bank_mask:0xf bound_ctrl:1
	s_nop 1
	v_add_f32_dpp v16, v16, v16 row_mirror row_mask:0xf bank_mask:0xf bound_ctrl:1
	s_nop 0
	v_readlane_b32 s2, v16, 16
	v_readlane_b32 s10, v16, 48
	v_readlane_b32 s0, v16, 0
	v_readlane_b32 s1, v16, 32
	v_mov_b32_e32 v16, s2
	v_mov_b32_e32 v17, s10
	v_pk_add_f32 v[16:17], s[0:1], v[16:17]
	s_mov_b32 s0, 0x800000
	v_add_f32_e32 v16, v16, v17
	v_fmamk_f32 v16, v16, 0x3a800000, v116
	v_cmp_gt_f32_e32 vcc, s0, v16
	v_mul_f32_e32 v17, 0x4b800000, v16
	s_nop 0
	v_cndmask_b32_e32 v16, v16, v17, vcc
	v_rsq_f32_e32 v54, v16
	ds_read_b128 v[16:19], v60 offset:53248
	s_waitcnt lgkmcnt(15)
	ds_read_b128 v[20:23], v60 offset:57344
	s_waitcnt lgkmcnt(15)
	ds_read_b128 v[24:27], v60 offset:61440
	s_waitcnt lgkmcnt(15)
	v_mul_f32_e32 v55, 0x45800000, v54
	v_cndmask_b32_e32 v98, v54, v55, vcc
	v_pk_mul_f32 v[28:29], v[28:29], v[98:99] op_sel_hi:[1,0]
	v_pk_fma_f32 v[106:107], v[30:31], v[28:29], v[34:35]
	v_pk_mul_f32 v[28:29], v[126:127], v[98:99] op_sel_hi:[1,0]
	s_waitcnt lgkmcnt(2)
	v_mul_f32_e32 v17, v107, v17
	v_pk_fma_f32 v[104:105], v[32:33], v[28:29], v[36:37]
	v_cvt_pk_bf16_f32 v28, v106, v107
	v_cvt_pk_bf16_f32 v29, v104, v105
	global_store_dwordx2 v[86:87], v[28:29], off offset:-1024
	v_mul_f32_e32 v28, v39, v107
	v_fmac_f32_e32 v28, v38, v106
	ds_read_b128 v[32:35], v234 offset:1024
	ds_read_b128 v[36:39], v234 offset:5120
	v_fmac_f32_e32 v28, v104, v40
	v_fmac_f32_e32 v28, v105, v41
	v_add_f32_e32 v54, 0, v28
	v_mul_f32_e32 v28, v107, v43
	v_fmac_f32_e32 v28, v106, v42
	v_fmac_f32_e32 v28, v104, v44
	v_fmac_f32_e32 v28, v105, v45
	v_add_f32_e32 v55, 0, v28
	v_mul_f32_e32 v28, v107, v47
	v_fmac_f32_e32 v28, v106, v46
	v_fmac_f32_e32 v28, v104, v48
	v_fmac_f32_e32 v28, v105, v49
	v_add_f32_e32 v46, 0, v28
	v_mul_f32_e32 v28, v107, v51
	v_fmac_f32_e32 v28, v106, v50
	v_fmac_f32_e32 v28, v104, v52
	v_fmac_f32_e32 v28, v105, v53
	v_add_f32_e32 v45, 0, v28
	v_mul_f32_e32 v28, v107, v109
	v_fmac_f32_e32 v28, v106, v108
	v_fmac_f32_e32 v28, v104, v110
	v_fmac_f32_e32 v28, v105, v111
	v_add_f32_e32 v44, 0, v28
	v_mul_f32_e32 v28, v107, v123
	v_fmac_f32_e32 v28, v106, v122
	v_fmac_f32_e32 v28, v104, v124
	v_fmac_f32_e32 v28, v105, v125
	v_add_f32_e32 v53, 0, v28
	v_mul_f32_e32 v28, v107, v131
	v_fmac_f32_e32 v28, v106, v130
	v_fmac_f32_e32 v28, v104, v132
	v_fmac_f32_e32 v28, v105, v133
	v_add_f32_e32 v52, 0, v28
	v_mul_f32_e32 v28, v107, v135
	v_fmac_f32_e32 v28, v106, v134
	v_fmac_f32_e32 v28, v104, v136
	v_fmac_f32_e32 v28, v105, v137
	v_add_f32_e32 v51, 0, v28
	v_mul_f32_e32 v28, v107, v139
	v_fmac_f32_e32 v28, v106, v138
	v_fmac_f32_e32 v28, v104, v140
	v_fmac_f32_e32 v28, v105, v141
	v_add_f32_e32 v50, 0, v28
	v_mul_f32_e32 v28, v107, v143
	v_fmac_f32_e32 v28, v106, v142
	v_fmac_f32_e32 v28, v104, v144
	v_fmac_f32_e32 v28, v105, v145
	v_add_f32_e32 v49, 0, v28
	v_mul_f32_e32 v28, v107, v147
	v_fmac_f32_e32 v28, v106, v146
	v_fmac_f32_e32 v28, v104, v148
	v_fmac_f32_e32 v28, v105, v149
	v_add_f32_e32 v48, 0, v28
	v_mul_f32_e32 v28, v107, v151
	v_fmac_f32_e32 v17, v106, v16
	s_waitcnt lgkmcnt(3)
	v_mul_f32_e32 v16, v107, v21
	v_fmac_f32_e32 v28, v106, v150
	v_fmac_f32_e32 v16, v106, v20
	v_fmac_f32_e32 v28, v104, v152
	v_fmac_f32_e32 v16, v104, v22
	v_fmac_f32_e32 v28, v105, v153
	v_fmac_f32_e32 v16, v105, v23
	v_add_f32_e32 v131, 0, v28
	v_mul_f32_e32 v28, v107, v155
	v_add_f32_e32 v122, 0, v16
	s_waitcnt lgkmcnt(2)
	v_mul_f32_e32 v16, v107, v25
	v_fmac_f32_e32 v28, v106, v154
	v_fmac_f32_e32 v16, v106, v24
	v_fmac_f32_e32 v28, v104, v156
	v_fmac_f32_e32 v17, v104, v18
	v_fmac_f32_e32 v16, v104, v26
	v_fmac_f32_e32 v28, v105, v157
	v_fmac_f32_e32 v17, v105, v19
	v_fmac_f32_e32 v16, v105, v27
	v_pk_mul_f32 v[40:41], v[158:159], v[98:99] op_sel_hi:[1,0]
	v_add_f32_e32 v125, 0, v28
	v_add_f32_e32 v124, 0, v17
	v_add_f32_e32 v123, 0, v16
	s_waitcnt lgkmcnt(0)
	v_pk_fma_f32 v[108:109], v[40:41], v[32:33], v[36:37]
	ds_read_b128 v[40:43], v60 offset:1024
	ds_read_b128 v[134:137], v60 offset:21504
	v_pk_mul_f32 v[32:33], v[160:161], v[98:99] op_sel_hi:[1,0]
	ds_read_b128 v[142:145], v60 offset:29696
	v_pk_fma_f32 v[110:111], v[32:33], v[34:35], v[38:39]
	s_waitcnt lgkmcnt(2)
	v_mul_f32_e32 v36, v109, v41
	v_cvt_pk_bf16_f32 v32, v108, v109
	v_cvt_pk_bf16_f32 v33, v110, v111
	v_fmac_f32_e32 v36, v108, v40
	global_store_dwordx2 v[86:87], v[32:33], off offset:-512
	ds_read_b128 v[32:35], v60 offset:5120
	v_fmac_f32_e32 v36, v110, v42
	v_fmac_f32_e32 v36, v111, v43
	v_add_f32_e32 v126, v54, v36
	s_waitcnt lgkmcnt(2)
	v_mul_f32_e32 v54, v109, v135
	s_waitcnt lgkmcnt(1)
	v_mul_f32_e32 v135, v109, v143
	v_fmac_f32_e32 v135, v108, v142
	v_fmac_f32_e32 v135, v110, v144
	v_fmac_f32_e32 v135, v111, v145
	ds_read_b128 v[144:147], v60 offset:50176
	s_waitcnt lgkmcnt(1)
	v_mul_f32_e32 v33, v109, v33
	v_fmac_f32_e32 v33, v108, v32
	v_fmac_f32_e32 v33, v110, v34
	v_fmac_f32_e32 v33, v111, v35
	ds_read_b128 v[36:39], v60 offset:9216
	v_add_f32_e32 v127, v55, v33
	ds_read_b128 v[32:35], v60 offset:13312
	ds_read_b128 v[40:43], v60 offset:17408
	ds_read_b128 v[138:141], v60 offset:25600
	v_fmac_f32_e32 v54, v108, v134
	v_fmac_f32_e32 v54, v110, v136
	s_waitcnt lgkmcnt(3)
	v_mul_f32_e32 v37, v109, v37
	s_waitcnt lgkmcnt(2)
	v_mul_f32_e32 v33, v109, v33
	v_fmac_f32_e32 v54, v111, v137
	v_fmac_f32_e32 v37, v108, v36
	v_fmac_f32_e32 v33, v108, v32
	v_add_f32_e32 v133, v53, v54
	s_waitcnt lgkmcnt(0)
	v_mul_f32_e32 v53, v109, v139
	v_fmac_f32_e32 v37, v110, v38
	v_fmac_f32_e32 v33, v110, v34
	v_mul_f32_e32 v41, v109, v41
	v_fmac_f32_e32 v53, v108, v138
	v_fmac_f32_e32 v37, v111, v39
	v_fmac_f32_e32 v33, v111, v35
	v_fmac_f32_e32 v41, v108, v40
	v_fmac_f32_e32 v53, v110, v140
	v_add_f32_e32 v129, v46, v37
	v_add_f32_e32 v130, v45, v33
	v_fmac_f32_e32 v41, v110, v42
	v_fmac_f32_e32 v53, v111, v141
	v_fmac_f32_e32 v41, v111, v43
	v_add_f32_e32 v134, v52, v53
	ds_read_b128 v[52:55], v60 offset:33792
	ds_read_b128 v[138:141], v60 offset:37888
	v_add_f32_e32 v132, v44, v41
	v_add_f32_e32 v135, v51, v135
	s_waitcnt lgkmcnt(1)
	v_mul_f32_e32 v51, v109, v53
	v_fmac_f32_e32 v51, v108, v52
	v_fmac_f32_e32 v51, v110, v54
	v_fmac_f32_e32 v51, v111, v55
	v_add_f32_e32 v136, v50, v51
	ds_read_b128 v[50:53], v60 offset:41984
	s_waitcnt lgkmcnt(1)
	v_mul_f32_e32 v54, v109, v139
	v_fmac_f32_e32 v54, v108, v138
	v_fmac_f32_e32 v54, v110, v140
	v_fmac_f32_e32 v54, v111, v141
	v_add_f32_e32 v137, v49, v54
	ds_read_b128 v[140:143], v60 offset:46080
	s_waitcnt lgkmcnt(1)
	v_mul_f32_e32 v49, v109, v51
	v_fmac_f32_e32 v49, v108, v50
	v_fmac_f32_e32 v49, v110, v52
	v_fmac_f32_e32 v49, v111, v53
	v_add_f32_e32 v138, v48, v49
	ds_read_b128 v[48:51], v234 offset:2048
	ds_read_b128 v[52:55], v234 offset:6144
	s_waitcnt lgkmcnt(2)
	v_mul_f32_e32 v139, v109, v141
	v_fmac_f32_e32 v139, v108, v140
	v_fmac_f32_e32 v139, v110, v142
	v_fmac_f32_e32 v139, v111, v143
	ds_read_b128 v[140:143], v60 offset:54272
	v_add_f32_e32 v131, v131, v139
	v_mul_f32_e32 v139, v109, v145
	v_fmac_f32_e32 v139, v108, v144
	v_fmac_f32_e32 v139, v110, v146
	v_fmac_f32_e32 v139, v111, v147
	ds_read_b128 v[144:147], v60 offset:58368
	v_add_f32_e32 v139, v125, v139
	s_waitcnt lgkmcnt(1)
	v_mul_f32_e32 v125, v109, v141
	v_fmac_f32_e32 v125, v108, v140
	v_fmac_f32_e32 v125, v110, v142
	v_fmac_f32_e32 v125, v111, v143
	ds_read_b128 v[140:143], v60 offset:62464
	v_add_f32_e32 v148, v124, v125
	s_waitcnt lgkmcnt(1)
	v_mul_f32_e32 v124, v109, v145
	v_fmac_f32_e32 v124, v108, v144
	v_fmac_f32_e32 v124, v110, v146
	v_fmac_f32_e32 v124, v111, v147
	v_add_f32_e32 v144, v122, v124
	s_waitcnt lgkmcnt(0)
	v_mul_f32_e32 v122, v109, v141
	v_fmac_f32_e32 v122, v108, v140
	v_fmac_f32_e32 v122, v110, v142
	v_fmac_f32_e32 v122, v111, v143
	v_add_f32_e32 v142, v123, v122
	v_mov_b32_e32 v122, v106
	v_mov_b32_e32 v123, v108
	v_mov_b32_e32 v108, v107
	v_mov_b32_e32 v106, v186
	v_mov_b32_e32 v124, v182
	v_mov_b32_e32 v140, v190
	v_mov_b32_e32 v125, v198
	v_mov_b32_e32 v107, v202
	v_pk_mul_f32 v[106:107], v[108:109], v[106:107]
	v_mov_b32_e32 v36, v187
	v_pk_fma_f32 v[106:107], v[122:123], v[124:125], v[106:107]
	v_mov_b32_e32 v124, v104
	v_mov_b32_e32 v125, v110
	v_mov_b32_e32 v110, v105
	v_mov_b32_e32 v104, v194
	v_mov_b32_e32 v141, v206
	v_pk_fma_f32 v[106:107], v[124:125], v[140:141], v[106:107]
	v_mov_b32_e32 v105, v210
	v_mov_b32_e32 v32, v183
	v_mov_b32_e32 v37, v203
	v_pk_mul_f32 v[24:25], v[108:109], v[36:37]
	v_pk_fma_f32 v[104:105], v[110:111], v[104:105], v[106:107]
	v_mov_b32_e32 v33, v199
	v_pk_fma_f32 v[24:25], v[122:123], v[32:33], v[24:25]
	v_mov_b32_e32 v40, v191
	v_add_f32_e32 v16, 0, v104
	v_mov_b32_e32 v41, v207
	v_pk_fma_f32 v[20:21], v[124:125], v[40:41], v[24:25]
	v_mov_b32_e32 v44, v195
	v_add_f32_e32 v107, v16, v105
	v_mov_b32_e32 v45, v211
	v_pk_fma_f32 v[16:17], v[110:111], v[44:45], v[20:21]
	v_mov_b32_e32 v20, v188
	v_add_f32_e32 v16, 0, v16
	v_mov_b32_e32 v21, v204
	v_add_f32_e32 v105, v16, v17
	v_mov_b32_e32 v16, v184
	v_mov_b32_e32 v17, v200
	v_pk_mul_f32 v[20:21], v[108:109], v[20:21]
	v_mov_b32_e32 v38, v189
	v_pk_fma_f32 v[16:17], v[122:123], v[16:17], v[20:21]
	v_mov_b32_e32 v20, v192
	v_mov_b32_e32 v21, v208
	v_pk_fma_f32 v[16:17], v[124:125], v[20:21], v[16:17]
	v_mov_b32_e32 v20, v196
	v_mov_b32_e32 v21, v212
	v_pk_fma_f32 v[16:17], v[110:111], v[20:21], v[16:17]
	v_mov_b32_e32 v34, v185
	v_add_f32_e32 v16, 0, v16
	v_add_f32_e32 v106, v16, v17
	v_mov_b32_e32 v39, v205
	v_pk_mul_f32 v[16:17], v[108:109], v[38:39]
	v_mov_b32_e32 v42, v193
	v_mov_b32_e32 v35, v201
	v_pk_fma_f32 v[16:17], v[122:123], v[34:35], v[16:17]
	v_mov_b32_e32 v46, v197
	v_mov_b32_e32 v43, v209
	v_pk_fma_f32 v[16:17], v[124:125], v[42:43], v[16:17]
	v_pk_mul_f32 v[20:21], v[102:103], v[98:99] op_sel_hi:[1,0]
	v_mov_b32_e32 v47, v213
	v_pk_fma_f32 v[16:17], v[110:111], v[46:47], v[16:17]
	v_pk_fma_f32 v[50:51], v[20:21], v[50:51], v[54:55]
	v_add_f32_e32 v16, 0, v16
	v_add_f32_e32 v104, v16, v17
	v_pk_mul_f32 v[16:17], v[100:101], v[98:99] op_sel_hi:[1,0]
	v_cvt_pk_bf16_f32 v21, v50, v51
	v_pk_fma_f32 v[48:49], v[16:17], v[48:49], v[52:53]
	ds_read_b128 v[16:19], v60 offset:2048
	v_cvt_pk_bf16_f32 v20, v48, v49
	global_store_dwordx2 v[86:87], v[20:21], off
	ds_read_b128 v[20:23], v60 offset:6144
	v_pk_mul_f32 v[46:47], v[94:95], v[98:99] op_sel_hi:[1,0]
	s_waitcnt lgkmcnt(1)
	v_mul_f32_e32 v17, v49, v17
	v_fmac_f32_e32 v17, v48, v16
	v_fmac_f32_e32 v17, v50, v18
	v_fmac_f32_e32 v17, v51, v19
	v_add_f32_e32 v42, v126, v17
	ds_read_b128 v[16:19], v60 offset:10240
	s_waitcnt lgkmcnt(1)
	v_mul_f32_e32 v21, v49, v21
	v_fmac_f32_e32 v21, v48, v20
	v_fmac_f32_e32 v21, v50, v22
	v_fmac_f32_e32 v21, v51, v23
	v_add_f32_e32 v41, v127, v21
	ds_read_b128 v[20:23], v60 offset:14336
	s_waitcnt lgkmcnt(1)
	v_mul_f32_e32 v17, v49, v17
	v_fmac_f32_e32 v17, v48, v16
	v_fmac_f32_e32 v17, v50, v18
	v_fmac_f32_e32 v17, v51, v19
	v_add_f32_e32 v40, v129, v17
	ds_read_b128 v[16:19], v60 offset:18432
	ds_read_b128 v[32:35], v234 offset:3072
	ds_read_b128 v[36:39], v234 offset:7168
	s_waitcnt lgkmcnt(3)
	v_mul_f32_e32 v21, v49, v21
	v_fmac_f32_e32 v21, v48, v20
	v_fmac_f32_e32 v21, v50, v22
	v_fmac_f32_e32 v21, v51, v23
	v_add_f32_e32 v45, v130, v21
	ds_read_b128 v[20:23], v60 offset:22528
	s_waitcnt lgkmcnt(3)
	v_mul_f32_e32 v17, v49, v17
	v_fmac_f32_e32 v17, v48, v16
	v_fmac_f32_e32 v17, v50, v18
	v_fmac_f32_e32 v17, v51, v19
	v_add_f32_e32 v44, v132, v17
	ds_read_b128 v[16:19], v60 offset:26624
	s_waitcnt lgkmcnt(1)
	v_mul_f32_e32 v21, v49, v21
	v_fmac_f32_e32 v21, v48, v20
	v_fmac_f32_e32 v21, v50, v22
	v_fmac_f32_e32 v21, v51, v23
	v_add_f32_e32 v124, v133, v21
	ds_read_b128 v[20:23], v60 offset:30720
	s_waitcnt lgkmcnt(1)
	v_mul_f32_e32 v17, v49, v17
	v_fmac_f32_e32 v17, v48, v16
	v_fmac_f32_e32 v17, v50, v18
	v_fmac_f32_e32 v17, v51, v19
	s_waitcnt lgkmcnt(0)
	v_mul_f32_e32 v21, v49, v21
	v_fmac_f32_e32 v21, v48, v20
	v_fmac_f32_e32 v21, v50, v22
	v_add_f32_e32 v123, v134, v17
	ds_read_b128 v[16:19], v60 offset:34816
	v_fmac_f32_e32 v21, v51, v23
	v_add_f32_e32 v122, v135, v21
	ds_read_b128 v[20:23], v60 offset:38912
	s_waitcnt lgkmcnt(1)
	v_mul_f32_e32 v17, v49, v17
	v_fmac_f32_e32 v17, v48, v16
	v_fmac_f32_e32 v17, v50, v18
	s_waitcnt lgkmcnt(0)
	v_mul_f32_e32 v21, v49, v21
	v_fmac_f32_e32 v21, v48, v20
	v_fmac_f32_e32 v17, v51, v19
	v_fmac_f32_e32 v21, v50, v22
	v_add_f32_e32 v111, v136, v17
	ds_read_b128 v[16:19], v60 offset:43008
	v_fmac_f32_e32 v21, v51, v23
	v_add_f32_e32 v110, v137, v21
	ds_read_b128 v[20:23], v60 offset:47104
	s_waitcnt lgkmcnt(1)
	v_mul_f32_e32 v17, v49, v17
	v_fmac_f32_e32 v17, v48, v16
	v_fmac_f32_e32 v17, v50, v18
	s_waitcnt lgkmcnt(0)
	v_mul_f32_e32 v21, v49, v21
	v_fmac_f32_e32 v21, v48, v20
	v_fmac_f32_e32 v17, v51, v19
	v_fmac_f32_e32 v21, v50, v22
	v_add_f32_e32 v109, v138, v17
	ds_read_b128 v[16:19], v60 offset:51200
	v_fmac_f32_e32 v21, v51, v23
	v_add_f32_e32 v108, v131, v21
	ds_read_b128 v[20:23], v60 offset:55296
	s_waitcnt lgkmcnt(1)
	v_mul_f32_e32 v17, v49, v17
	v_fmac_f32_e32 v17, v48, v16
	v_fmac_f32_e32 v17, v50, v18
	s_waitcnt lgkmcnt(0)
	v_mul_f32_e32 v21, v49, v21
	v_fmac_f32_e32 v21, v48, v20
	v_fmac_f32_e32 v17, v51, v19
	v_fmac_f32_e32 v21, v50, v22
	v_add_f32_e32 v103, v139, v17
	ds_read_b128 v[16:19], v60 offset:59392
	v_fmac_f32_e32 v21, v51, v23
	v_add_f32_e32 v102, v148, v21
	ds_read_b128 v[20:23], v60 offset:63488
	s_waitcnt lgkmcnt(1)
	v_mul_f32_e32 v17, v49, v17
	v_fmac_f32_e32 v17, v48, v16
	v_fmac_f32_e32 v17, v50, v18
	s_waitcnt lgkmcnt(0)
	v_mul_f32_e32 v16, v49, v21
	v_fmac_f32_e32 v16, v48, v20
	v_fmac_f32_e32 v16, v50, v22
	v_fmac_f32_e32 v17, v51, v19
	v_fmac_f32_e32 v16, v51, v23
	v_add_f32_e32 v100, v144, v17
	v_add_f32_e32 v101, v142, v16
	v_pk_fma_f32 v[52:53], v[46:47], v[32:33], v[36:37]
	v_pk_mul_f32 v[32:33], v[96:97], v[98:99] op_sel_hi:[1,0]
	ds_read_b128 v[94:97], v60 offset:3072
	v_pk_fma_f32 v[54:55], v[32:33], v[34:35], v[38:39]
	v_cvt_pk_bf16_f32 v32, v52, v53
	v_cvt_pk_bf16_f32 v33, v54, v55
	global_store_dwordx2 v[86:87], v[32:33], off offset:512
	ds_read_b128 v[32:35], v60 offset:7168
	s_waitcnt lgkmcnt(1)
	v_mul_f32_e32 v36, v53, v95
	v_fmac_f32_e32 v36, v52, v94
	v_fmac_f32_e32 v36, v54, v96
	v_fmac_f32_e32 v36, v55, v97
	v_add_f32_e32 v94, v42, v36
	ds_read_b128 v[36:39], v60 offset:11264
	ds_read_b128 v[130:133], v60 offset:15360
	s_waitcnt lgkmcnt(2)
	v_mul_f32_e32 v33, v53, v33
	v_fmac_f32_e32 v33, v52, v32
	v_fmac_f32_e32 v33, v54, v34
	s_waitcnt lgkmcnt(1)
	v_mul_f32_e32 v32, v53, v37
	v_fmac_f32_e32 v32, v52, v36
	v_fmac_f32_e32 v32, v54, v38
	v_fmac_f32_e32 v33, v55, v35
	v_fmac_f32_e32 v32, v55, v39
	v_add_f32_e32 v95, v41, v33
	v_add_f32_e32 v96, v40, v32
	ds_read_b128 v[40:43], v60 offset:19456
	s_waitcnt lgkmcnt(1)
	v_mul_f32_e32 v36, v53, v131
	v_fmac_f32_e32 v36, v52, v130
	v_fmac_f32_e32 v36, v54, v132
	v_fmac_f32_e32 v36, v55, v133
	v_add_f32_e32 v97, v45, v36
	ds_read_b128 v[130:133], v60 offset:23552
	s_waitcnt lgkmcnt(1)
	v_mul_f32_e32 v45, v53, v41
	v_fmac_f32_e32 v45, v52, v40
	v_fmac_f32_e32 v45, v54, v42
	v_fmac_f32_e32 v45, v55, v43
	v_add_f32_e32 v125, v44, v45
	ds_read_b128 v[134:137], v60 offset:27648
	s_waitcnt lgkmcnt(1)
	v_mul_f32_e32 v98, v53, v131
	v_fmac_f32_e32 v98, v52, v130
	v_fmac_f32_e32 v98, v54, v132
	v_fmac_f32_e32 v98, v55, v133
	ds_read_b128 v[130:133], v60 offset:31744
	v_add_f32_e32 v124, v124, v98
	s_waitcnt lgkmcnt(1)
	v_mul_f32_e32 v98, v53, v135
	v_fmac_f32_e32 v98, v52, v134
	v_fmac_f32_e32 v98, v54, v136
	v_fmac_f32_e32 v98, v55, v137
	ds_read_b128 v[134:137], v60 offset:35840
	v_add_f32_e32 v98, v123, v98
	s_waitcnt lgkmcnt(1)
	v_mul_f32_e32 v123, v53, v131
	v_fmac_f32_e32 v123, v52, v130
	v_fmac_f32_e32 v123, v54, v132
	v_fmac_f32_e32 v123, v55, v133
	ds_read_b128 v[130:133], v60 offset:39936
	v_add_f32_e32 v122, v122, v123
	s_waitcnt lgkmcnt(1)
	v_mul_f32_e32 v123, v53, v135
	v_fmac_f32_e32 v123, v52, v134
	v_fmac_f32_e32 v123, v54, v136
	v_fmac_f32_e32 v123, v55, v137
	ds_read_b128 v[134:137], v60 offset:44032
	v_add_f32_e32 v111, v111, v123
	s_waitcnt lgkmcnt(1)
	v_mul_f32_e32 v123, v53, v131
	v_fmac_f32_e32 v123, v52, v130
	v_fmac_f32_e32 v123, v54, v132
	v_fmac_f32_e32 v123, v55, v133
	ds_read_b128 v[130:133], v60 offset:48128
	v_add_f32_e32 v110, v110, v123
	s_waitcnt lgkmcnt(1)
	v_mul_f32_e32 v123, v53, v135
	v_fmac_f32_e32 v123, v52, v134
	v_fmac_f32_e32 v123, v54, v136
	v_fmac_f32_e32 v123, v55, v137
	ds_read_b128 v[134:137], v60 offset:52224
	v_add_f32_e32 v109, v109, v123
	s_waitcnt lgkmcnt(1)
	v_mul_f32_e32 v123, v53, v131
	v_fmac_f32_e32 v123, v52, v130
	v_fmac_f32_e32 v123, v54, v132
	v_fmac_f32_e32 v123, v55, v133
	ds_read_b128 v[130:133], v60 offset:56320
	v_add_f32_e32 v108, v108, v123
	s_waitcnt lgkmcnt(1)
	v_mul_f32_e32 v123, v53, v135
	v_fmac_f32_e32 v123, v52, v134
	v_fmac_f32_e32 v123, v54, v136
	v_fmac_f32_e32 v123, v55, v137
	ds_read_b128 v[134:137], v60 offset:60416
	v_add_f32_e32 v103, v103, v123
	s_waitcnt lgkmcnt(1)
	v_mul_f32_e32 v123, v53, v131
	v_fmac_f32_e32 v123, v52, v130
	v_fmac_f32_e32 v123, v54, v132
	v_fmac_f32_e32 v123, v55, v133
	ds_read_b128 v[130:133], v60 offset:64512
	v_add_f32_e32 v102, v102, v123
	s_waitcnt lgkmcnt(1)
	v_mul_f32_e32 v123, v53, v135
	v_fmac_f32_e32 v123, v52, v134
	v_fmac_f32_e32 v123, v54, v136
	v_fmac_f32_e32 v123, v55, v137
	v_add_f32_e32 v123, v100, v123
	s_waitcnt lgkmcnt(0)
	v_mul_f32_e32 v100, v53, v131
	v_fmac_f32_e32 v100, v52, v130
	v_fmac_f32_e32 v100, v54, v132
	v_fmac_f32_e32 v100, v55, v133
	v_add_f32_e32 v129, v101, v100
	v_mov_b32_e32 v100, v48
	v_mov_b32_e32 v101, v52
	v_mov_b32_e32 v52, v49
	v_mov_b32_e32 v48, v218
	v_mov_b32_e32 v126, v214
	v_mov_b32_e32 v130, v222
	v_mov_b32_e32 v127, v230
	v_mov_b32_e32 v49, v238
	v_pk_mul_f32 v[48:49], v[52:53], v[48:49]
	v_mov_b32_e32 v36, v219
	v_pk_fma_f32 v[48:49], v[100:101], v[126:127], v[48:49]
	v_mov_b32_e32 v126, v50
	v_mov_b32_e32 v127, v54
	v_mov_b32_e32 v131, v242
	v_pk_fma_f32 v[48:49], v[126:127], v[130:131], v[48:49]
	v_mov_b32_e32 v54, v51
	v_mov_b32_e32 v50, v226
	v_mov_b32_e32 v51, v246
	v_mov_b32_e32 v32, v215
	v_mov_b32_e32 v37, v239
	v_pk_mul_f32 v[24:25], v[52:53], v[36:37]
	v_pk_fma_f32 v[48:49], v[54:55], v[50:51], v[48:49]
	v_mov_b32_e32 v33, v231
	v_pk_fma_f32 v[24:25], v[100:101], v[32:33], v[24:25]
	v_mov_b32_e32 v40, v223
	v_add_f32_e32 v16, v107, v48
	v_mov_b32_e32 v41, v243
	v_pk_fma_f32 v[20:21], v[126:127], v[40:41], v[24:25]
	v_mov_b32_e32 v44, v227
	v_add_f32_e32 v28, v16, v49
	v_mov_b32_e32 v45, v247
	v_pk_fma_f32 v[16:17], v[54:55], v[44:45], v[20:21]
	v_mov_b32_e32 v20, v220
	v_add_f32_e32 v16, v105, v16
	v_mov_b32_e32 v21, v240
	v_add_f32_e32 v24, v16, v17
	v_mov_b32_e32 v16, v216
	v_mov_b32_e32 v17, v232
	v_pk_mul_f32 v[20:21], v[52:53], v[20:21]
	v_mov_b32_e32 v38, v221
	v_pk_fma_f32 v[16:17], v[100:101], v[16:17], v[20:21]
	v_mov_b32_e32 v20, v224
	v_mov_b32_e32 v21, v244
	v_pk_fma_f32 v[16:17], v[126:127], v[20:21], v[16:17]
	v_mov_b32_e32 v20, v228
	v_mov_b32_e32 v21, v248
	v_pk_fma_f32 v[16:17], v[54:55], v[20:21], v[16:17]
	v_mov_b32_e32 v34, v217
	v_add_f32_e32 v16, v106, v16
	v_add_f32_e32 v20, v16, v17
	v_mov_b32_e32 v39, v241
	v_pk_mul_f32 v[16:17], v[52:53], v[38:39]
	v_mov_b32_e32 v42, v225
	v_mov_b32_e32 v35, v233
	v_pk_fma_f32 v[16:17], v[100:101], v[34:35], v[16:17]
	v_mov_b32_e32 v46, v229
	v_mov_b32_e32 v43, v245
	v_pk_fma_f32 v[16:17], v[126:127], v[42:43], v[16:17]
	v_mov_b32_e32 v47, v249
	v_pk_fma_f32 v[16:17], v[54:55], v[46:47], v[16:17]
	v_add_f32_e32 v16, v104, v16
	v_add_f32_e32 v22, v16, v17
	v_add_f32_dpp v250, v24, v24 row_mirror row_mask:0xf bank_mask:0xf bound_ctrl:1
	v_add_f32_dpp v94, v94, v94 row_mirror row_mask:0xf bank_mask:0xf bound_ctrl:1
	v_add_f32_dpp v125, v125, v125 row_mirror row_mask:0xf bank_mask:0xf bound_ctrl:1
	v_add_f32_dpp v111, v111, v111 row_mirror row_mask:0xf bank_mask:0xf bound_ctrl:1
	v_add_f32_dpp v103, v103, v103 row_mirror row_mask:0xf bank_mask:0xf bound_ctrl:1
	v_add_f32_dpp v250, v20, v20 row_mirror row_mask:0xf bank_mask:0xc bound_ctrl:1
	v_add_f32_dpp v94, v95, v95 row_mirror row_mask:0xf bank_mask:0xc bound_ctrl:1
	v_add_f32_dpp v125, v124, v124 row_mirror row_mask:0xf bank_mask:0xc bound_ctrl:1
	v_add_f32_dpp v111, v110, v110 row_mirror row_mask:0xf bank_mask:0xc bound_ctrl:1
	v_add_f32_dpp v103, v102, v102 row_mirror row_mask:0xf bank_mask:0xc bound_ctrl:1
	v_add_f32_dpp v251, v28, v28 row_mirror row_mask:0xf bank_mask:0xf bound_ctrl:1
	v_add_f32_dpp v96, v96, v96 row_mirror row_mask:0xf bank_mask:0xf bound_ctrl:1
	v_add_f32_dpp v98, v98, v98 row_mirror row_mask:0xf bank_mask:0xf bound_ctrl:1
	v_add_f32_dpp v109, v109, v109 row_mirror row_mask:0xf bank_mask:0xf bound_ctrl:1
	v_add_f32_dpp v123, v123, v123 row_mirror row_mask:0xf bank_mask:0xf bound_ctrl:1
	v_add_f32_dpp v251, v22, v22 row_mirror row_mask:0xf bank_mask:0xc bound_ctrl:1
	v_add_f32_dpp v96, v97, v97 row_mirror row_mask:0xf bank_mask:0xc bound_ctrl:1
	v_add_f32_dpp v98, v122, v122 row_mirror row_mask:0xf bank_mask:0xc bound_ctrl:1
	v_add_f32_dpp v109, v108, v108 row_mirror row_mask:0xf bank_mask:0xc bound_ctrl:1
	v_add_f32_dpp v123, v129, v129 row_mirror row_mask:0xf bank_mask:0xc bound_ctrl:1
	v_add_f32_dpp v250, v250, v250 row_half_mirror row_mask:0xf bank_mask:0xf bound_ctrl:1
	v_add_f32_dpp v94, v94, v94 row_half_mirror row_mask:0xf bank_mask:0xf bound_ctrl:1
	v_add_f32_dpp v125, v125, v125 row_half_mirror row_mask:0xf bank_mask:0xf bound_ctrl:1
	v_add_f32_dpp v111, v111, v111 row_half_mirror row_mask:0xf bank_mask:0xf bound_ctrl:1
	v_add_f32_dpp v103, v103, v103 row_half_mirror row_mask:0xf bank_mask:0xf bound_ctrl:1
	v_add_f32_dpp v250, v251, v251 row_half_mirror row_mask:0xf bank_mask:0xa bound_ctrl:1
	v_add_f32_dpp v94, v96, v96 row_half_mirror row_mask:0xf bank_mask:0xa bound_ctrl:1
	v_add_f32_dpp v125, v98, v98 row_half_mirror row_mask:0xf bank_mask:0xa bound_ctrl:1
	v_add_f32_dpp v111, v109, v109 row_half_mirror row_mask:0xf bank_mask:0xa bound_ctrl:1
	v_add_f32_dpp v103, v123, v123 row_half_mirror row_mask:0xf bank_mask:0xa bound_ctrl:1
	v_add_f32_dpp v250, v250, v250 quad_perm:[1,0,3,2] row_mask:0xf bank_mask:0xf bound_ctrl:1
	v_add_f32_dpp v94, v94, v94 quad_perm:[1,0,3,2] row_mask:0xf bank_mask:0xf bound_ctrl:1
	v_add_f32_dpp v125, v125, v125 quad_perm:[1,0,3,2] row_mask:0xf bank_mask:0xf bound_ctrl:1
	v_add_f32_dpp v111, v111, v111 quad_perm:[1,0,3,2] row_mask:0xf bank_mask:0xf bound_ctrl:1
	v_add_f32_dpp v103, v103, v103 quad_perm:[1,0,3,2] row_mask:0xf bank_mask:0xf bound_ctrl:1
	v_add_f32_dpp v250, v250, v250 quad_perm:[2,3,0,1] row_mask:0xf bank_mask:0xf bound_ctrl:1
	v_add_f32_dpp v94, v94, v94 quad_perm:[2,3,0,1] row_mask:0xf bank_mask:0xf bound_ctrl:1
	v_add_f32_dpp v125, v125, v125 quad_perm:[2,3,0,1] row_mask:0xf bank_mask:0xf bound_ctrl:1
	v_add_f32_dpp v111, v111, v111 quad_perm:[2,3,0,1] row_mask:0xf bank_mask:0xf bound_ctrl:1
	v_add_f32_dpp v103, v103, v103 quad_perm:[2,3,0,1] row_mask:0xf bank_mask:0xf bound_ctrl:1
	v_readlane_b32 s2, v250, 20
	v_readlane_b32 s10, v250, 52
	v_readlane_b32 s0, v250, 4
	v_readlane_b32 s1, v250, 36
	v_mov_b32_e32 v16, s2
	v_mov_b32_e32 v17, s10
	v_readlane_b32 s2, v250, 16
	v_readlane_b32 s10, v250, 48
	v_pk_add_f32 v[16:17], s[0:1], v[16:17]
	v_readlane_b32 s0, v250, 0
	v_readlane_b32 s1, v250, 32
	v_mov_b32_e32 v18, s2
	v_mov_b32_e32 v19, s10
	v_readlane_b32 s2, v250, 24
	v_readlane_b32 s10, v250, 56
	v_pk_add_f32 v[18:19], s[0:1], v[18:19]
	v_readlane_b32 s0, v250, 8
	v_readlane_b32 s1, v250, 40
	v_mov_b32_e32 v20, s2
	v_mov_b32_e32 v21, s10
	v_pk_add_f32 v[20:21], s[0:1], v[20:21]
	v_mov_b32_e32 v25, v18
	v_add_f32_e32 v26, v20, v21
	v_mov_b32_e32 v18, v17
	v_readlane_b32 s2, v250, 28
	v_readlane_b32 s10, v250, 60
	v_readlane_b32 s0, v250, 12
	v_readlane_b32 s1, v250, 44
	v_mov_b32_e32 v20, s2
	v_mov_b32_e32 v21, s10
	v_pk_add_f32 v[20:21], s[0:1], v[20:21]
	v_add_f32_e32 v27, v20, v21
	v_readlane_b32 s14, v94, 0
	v_readlane_b32 s94, v94, 16
	v_readlane_b32 s15, v94, 32
	v_readlane_b32 s95, v94, 48
	v_readlane_b32 s87, v94, 8
	v_readlane_b32 s91, v94, 24
	v_readlane_b32 s90, v94, 40
	v_readlane_b32 s92, v94, 56
	v_readlane_b32 s65, v94, 4
	v_readlane_b32 s75, v94, 20
	v_readlane_b32 s66, v94, 36
	v_readlane_b32 s78, v94, 52
	v_readlane_b32 s51, v94, 12
	v_readlane_b32 s53, v94, 28
	v_readlane_b32 s52, v94, 44
	v_readlane_b32 s54, v94, 60
	v_readlane_b32 s35, v125, 0
	v_readlane_b32 s37, v125, 16
	v_readlane_b32 s36, v125, 32
	v_readlane_b32 s38, v125, 48
	v_readlane_b32 s23, v125, 8
	v_readlane_b32 s27, v125, 24
	v_readlane_b32 s26, v125, 40
	v_readlane_b32 s93, v125, 56
	v_readlane_b32 s81, v125, 4
	v_readlane_b32 s83, v125, 20
	v_readlane_b32 s82, v125, 36
	v_readlane_b32 s84, v125, 52
	v_readlane_b32 s63, v125, 12
	v_readlane_b32 s67, v125, 28
	v_readlane_b32 s64, v125, 44
	v_readlane_b32 s70, v125, 60
	v_readlane_b32 s59, v111, 0
	v_readlane_b32 s61, v111, 16
	v_readlane_b32 s60, v111, 32
	v_readlane_b32 s62, v111, 48
	v_readlane_b32 s55, v111, 8
	v_readlane_b32 s57, v111, 24
	v_readlane_b32 s56, v111, 40
	v_readlane_b32 s58, v111, 56
	v_readlane_b32 s47, v111, 4
	v_readlane_b32 s49, v111, 20
	v_readlane_b32 s48, v111, 36
	v_readlane_b32 s50, v111, 52
	v_readlane_b32 s43, v111, 12
	v_readlane_b32 s45, v111, 28
	v_readlane_b32 s44, v111, 44
	v_readlane_b32 s46, v111, 60
	v_readlane_b32 s39, v103, 0
	v_readlane_b32 s41, v103, 16
	v_readlane_b32 s40, v103, 32
	v_readlane_b32 s42, v103, 48
	v_readlane_b32 s30, v103, 8
	v_readlane_b32 s33, v103, 24
	v_readlane_b32 s31, v103, 40
	v_readlane_b32 s34, v103, 56
	v_readlane_b32 s28, v103, 4
	v_readlane_b32 s29, v103, 20
	v_readlane_b32 s85, v103, 36
	v_readlane_b32 s86, v103, 52
	v_mov_b32_e32 v24, v16
	v_pk_add_f32 v[16:17], v[24:25], v[18:19]
	v_mov_b32_e32 v20, v178
	v_mov_b32_e32 v21, v179
	v_mov_b32_e32 v22, v180
	v_mov_b32_e32 v23, v181
	v_add_f32_e32 v19, v26, v22
	v_pk_add_f32 v[16:17], v[16:17], v[20:21]
	v_add_f32_e32 v18, v27, v23
	v_cmp_gt_f32_e32 vcc, v17, v16
	v_mov_b32_e32 v22, 0
	v_readlane_b32 s71, v103, 12
	v_cndmask_b32_e32 v20, v16, v17, vcc
	v_cmp_gt_f32_e64 s[12:13], v19, v20
	v_cndmask_b32_e64 v21, 0, 1, vcc
	s_and_b64 s[10:11], s[12:13], exec
	v_cndmask_b32_e64 v20, v20, v19, s[12:13]
	v_cmp_ngt_f32_e64 s[0:1], v18, v20
	v_readfirstlane_b32 s2, v21
	s_cselect_b32 s2, 2, s2
	s_and_b64 s[10:11], s[0:1], exec
	s_cselect_b32 s2, s2, 3
	s_cmp_eq_u32 s2, 0
	s_cselect_b64 s[24:25], -1, 0
	s_cmp_lg_u32 s2, 0
	v_mov_b32_e32 v21, 0
	v_readlane_b32 s79, v103, 28
	v_readlane_b32 s74, v103, 44
	v_readlane_b32 s80, v103, 60
	v_cmp_gt_f32_e64 s[10:11], v18, v20
	s_waitcnt lgkmcnt(0)
	s_cbranch_scc0 .LBB0_1684
	v_cndmask_b32_e64 v23, 0, 1, s[24:25]
	v_cmp_ne_u32_e64 s[14:15], 1, v23
	s_andn2_b64 vcc, exec, s[24:25]
	s_cbranch_vccz .LBB0_1685
